# xg (next-operand) stores of the residual epilogues written through (sc1); x stores unchanged
# speedup vs baseline: 1.0005x; 1.0005x over previous
.LBB0_598:
	v_mbcnt_lo_u32_b32 v64, -1, 0
	v_mbcnt_hi_u32_b32 v64, -1, v64
	s_add_i32 s15, s15, s57
	v_ashrrev_i32_e32 v65, 1, v64
	v_and_or_b32 v242, v64, 15, s15
	s_or_b32 s2, s88, s60
	v_and_b32_e32 v65, -8, v65
	v_lshlrev_b32_e32 v220, 13, v242
	v_add_lshl_u32 v241, s2, v65, 1
	v_add_u32_e32 v221, v241, v220
	global_load_dwordx4 v[244:247], v221, s[4:5]
	s_add_i32 s24, s24, s96
	v_cmp_gt_u32_e32 vcc, 16, v64
	v_add_lshl_u32 v64, v65, s60, 2
	v_add_u32_e32 v243, s24, v64
	v_add_u32_e32 v64, 0x100, v221
	global_load_dwordx4 v[248:251], v64, s[4:5]
	v_add_u32_e32 v65, 0x20000, v221
	v_add_u32_e32 v66, 0x20100, v221
	v_add_u32_e32 v67, 0x40000, v221
	v_add_u32_e32 v72, 0x40100, v221
	v_add_u32_e32 v64, 0x60000, v221
	v_add_u32_e32 v73, 0x60100, v221
	v_add_u32_e32 v74, 0x100000, v221
	v_add_u32_e32 v75, 0x100100, v221
	v_add_u32_e32 v88, 0x120000, v221
	v_add_u32_e32 v89, 0x120100, v221
	v_add_u32_e32 v90, 0x140000, v221
	v_add_u32_e32 v91, 0x140100, v221
	v_add_u32_e32 v152, 0x160000, v221
	v_add_u32_e32 v153, 0x160100, v221
	global_load_dwordx4 v[212:215], v65, s[4:5]
	global_load_dwordx4 v[208:211], v66, s[4:5]
	global_load_dwordx4 v[204:207], v67, s[4:5]
	global_load_dwordx4 v[200:203], v72, s[4:5]
	global_load_dwordx4 v[192:195], v64, s[4:5]
	global_load_dwordx4 v[164:167], v73, s[4:5]
	global_load_dwordx4 v[140:143], v74, s[4:5]
	global_load_dwordx4 v[128:131], v75, s[4:5]
	global_load_dwordx4 v[116:119], v88, s[4:5]
	global_load_dwordx4 v[108:111], v89, s[4:5]
	global_load_dwordx4 v[96:99], v90, s[4:5]
	s_nop 0
	global_load_dwordx4 v[88:91], v91, s[4:5]
	s_nop 0
	global_load_dwordx4 v[72:75], v152, s[4:5]
	global_load_dwordx4 v[64:67], v153, s[4:5]
	s_waitcnt vmcnt(0)
	ds_read_b128 v[196:199], v243
	ds_read_b128 v[188:191], v243 offset:16
	ds_read_b128 v[184:187], v243 offset:4096
	ds_read_b128 v[180:183], v243 offset:4112
	ds_read_b128 v[168:171], v243 offset:512
	ds_read_b128 v[160:163], v243 offset:528
	ds_read_b128 v[156:159], v243 offset:4608
	ds_read_b128 v[152:155], v243 offset:4624
	v_lshlrev_b32_e32 v235, 12, v242
	s_waitcnt vmcnt(0)
	v_lshlrev_b32_e32 v218, 16, v244
	v_and_b32_e32 v219, 0xffff0000, v244
	v_lshlrev_b32_e32 v252, 16, v246
	v_and_b32_e32 v253, 0xffff0000, v246
	v_lshlrev_b32_e32 v246, 16, v247
	v_and_b32_e32 v247, 0xffff0000, v247
	v_lshlrev_b32_e32 v244, 16, v245
	v_and_b32_e32 v245, 0xffff0000, v245
	s_waitcnt lgkmcnt(7)
	v_pk_fma_f32 v[176:177], v[176:177], v[196:197], v[218:219]
	s_waitcnt lgkmcnt(6)
	v_pk_fma_f32 v[218:219], v[174:175], v[190:191], v[246:247]
	v_pk_fma_f32 v[174:175], v[172:173], v[188:189], v[252:253]
	v_pk_fma_f32 v[178:179], v[178:179], v[198:199], v[244:245]
	v_cvt_pk_bf16_f32 v172, v176, v177
	s_nop 0
	v_cvt_pk_bf16_f32 v173, v178, v179
	v_cvt_pk_bf16_f32 v174, v174, v175
	v_cvt_pk_bf16_f32 v175, v218, v219
	global_store_dwordx4 v221, v[172:175], s[4:5]
	v_lshlrev_b32_e32 v176, 16, v172
	v_and_b32_e32 v177, 0xffff0000, v172
	v_lshlrev_b32_e32 v172, 16, v173
	v_and_b32_e32 v173, 0xffff0000, v173
	v_lshlrev_b32_e32 v178, 16, v174
	v_and_b32_e32 v179, 0xffff0000, v174
	v_lshlrev_b32_e32 v174, 16, v175
	v_and_b32_e32 v175, 0xffff0000, v175
	v_mul_f32_e32 v221, v177, v177
	v_mul_f32_e32 v236, v173, v173
	v_mul_f32_e32 v252, v179, v179
	v_mul_f32_e32 v253, v175, v175
	v_fmac_f32_e32 v221, v176, v176
	v_fmac_f32_e32 v236, v172, v172
	v_fmac_f32_e32 v252, v178, v178
	v_fmac_f32_e32 v253, v174, v174
	s_waitcnt lgkmcnt(5)
	v_pk_mul_f32 v[218:219], v[186:187], v[172:173]
	v_add_f32_e32 v172, v221, v236
	v_add_f32_e32 v173, v252, v253
	v_pk_mul_f32 v[244:245], v[184:185], v[176:177]
	s_waitcnt lgkmcnt(4)
	v_pk_mul_f32 v[246:247], v[182:183], v[174:175]
	v_add_f32_e32 v221, v172, v173
	v_pk_mul_f32 v[174:175], v[180:181], v[178:179]
	v_cvt_pk_bf16_f32 v172, v244, v245
	v_cvt_pk_bf16_f32 v173, v218, v219
	v_add_u32_e32 v176, v241, v235
	v_cvt_pk_bf16_f32 v174, v174, v175
	v_cvt_pk_bf16_f32 v175, v246, v247
	global_store_dwordx4 v176, v[172:175], s[22:23] sc1
	v_lshlrev_b32_e32 v176, 16, v250
	v_and_b32_e32 v177, 0xffff0000, v250
	v_lshlrev_b32_e32 v172, 16, v248
	v_and_b32_e32 v173, 0xffff0000, v248
	v_lshlrev_b32_e32 v174, 16, v249
	v_and_b32_e32 v175, 0xffff0000, v249
	v_lshlrev_b32_e32 v178, 16, v251
	v_and_b32_e32 v179, 0xffff0000, v251
	s_waitcnt lgkmcnt(3)
	v_pk_fma_f32 v[148:149], v[148:149], v[168:169], v[172:173]
	s_waitcnt lgkmcnt(2)
	v_pk_fma_f32 v[144:145], v[144:145], v[160:161], v[176:177]
	v_pk_fma_f32 v[150:151], v[150:151], v[170:171], v[174:175]
	v_pk_fma_f32 v[172:173], v[146:147], v[162:163], v[178:179]
	v_cvt_pk_bf16_f32 v146, v148, v149
	v_cvt_pk_bf16_f32 v147, v150, v151
	v_cvt_pk_bf16_f32 v148, v144, v145
	v_add_u32_e32 v144, 0x100, v241
	v_add_u32_e32 v145, v144, v220
	v_cvt_pk_bf16_f32 v149, v172, v173
	global_store_dwordx4 v145, v[146:149], s[4:5]
	v_lshlrev_b32_e32 v150, 16, v146
	v_and_b32_e32 v151, 0xffff0000, v146
	v_lshlrev_b32_e32 v146, 16, v147
	v_and_b32_e32 v147, 0xffff0000, v147
	v_mul_f32_e32 v174, v151, v151
	v_mul_f32_e32 v175, v147, v147
	v_lshlrev_b32_e32 v172, 16, v148
	v_and_b32_e32 v173, 0xffff0000, v148
	v_lshlrev_b32_e32 v148, 16, v149
	v_and_b32_e32 v149, 0xffff0000, v149
	v_fmac_f32_e32 v174, v150, v150
	v_fmac_f32_e32 v175, v146, v146
	v_add_f32_e32 v174, v174, v175
	v_mul_f32_e32 v175, v173, v173
	v_mul_f32_e32 v176, v149, v149
	v_fmac_f32_e32 v175, v172, v172
	v_fmac_f32_e32 v176, v148, v148
	v_add_f32_e32 v175, v175, v176
	v_add_f32_e32 v174, v174, v175
	v_add_f32_e32 v176, v221, v174
	s_waitcnt lgkmcnt(1)
	v_pk_mul_f32 v[174:175], v[158:159], v[146:147]
	v_pk_mul_f32 v[146:147], v[156:157], v[150:151]
	s_waitcnt lgkmcnt(0)
	v_pk_mul_f32 v[150:151], v[154:155], v[148:149]
	v_pk_mul_f32 v[148:149], v[152:153], v[172:173]
	ds_swizzle_b32 v172, v176 offset:swizzle(SWAP,16)
	v_sub_u32_e32 v145, v145, v235
	v_cvt_pk_bf16_f32 v146, v146, v147
	v_cvt_pk_bf16_f32 v147, v174, v175
	v_cvt_pk_bf16_f32 v148, v148, v149
	v_cvt_pk_bf16_f32 v149, v150, v151
	global_store_dwordx4 v145, v[146:149], s[22:23] sc1
	s_waitcnt lgkmcnt(0)
	v_add_f32_e32 v145, v176, v172
	v_mov_b32_e32 v146, v145
	s_nop 1
	v_permlane32_swap_b32_e32 v145, v146
	s_and_saveexec_b64 s[88:89], vcc
	s_cbranch_execz .LBB0_600
	v_add_f32_e32 v145, v145, v146
	s_mov_b32 s2, 0x47800000
	v_fma_f32 v145, v145, s2, 0.5
	v_trunc_f32_e32 v145, v145
	v_mul_f32_e32 v146, 0x2f800000, v145
	v_floor_f32_e32 v147, v146
	v_fmac_f32_e32 v145, 0xcf800000, v147
	v_cvt_u32_f32_e32 v146, v145
	v_cvt_u32_f32_e32 v147, v147
	v_lshlrev_b32_e32 v145, 3, v242
	global_atomic_add_x2 v145, v[146:147], s[6:7]
.LBB0_600:
	s_or_b64 exec, exec, s[88:89]
	v_or_b32_e32 v145, 16, v242
	v_lshlrev_b32_e32 v174, 13, v145
	v_lshlrev_b32_e32 v146, 16, v212
	v_and_b32_e32 v147, 0xffff0000, v212
	v_lshlrev_b32_e32 v148, 16, v213
	v_and_b32_e32 v149, 0xffff0000, v213
	v_lshlrev_b32_e32 v150, 16, v214
	v_and_b32_e32 v151, 0xffff0000, v214
	v_lshlrev_b32_e32 v172, 16, v215
	v_and_b32_e32 v173, 0xffff0000, v215
	v_pk_fma_f32 v[138:139], v[138:139], v[198:199], v[148:149]
	v_pk_fma_f32 v[136:137], v[136:137], v[196:197], v[146:147]
	v_pk_fma_f32 v[146:147], v[134:135], v[190:191], v[172:173]
	v_pk_fma_f32 v[134:135], v[132:133], v[188:189], v[150:151]
	v_cvt_pk_bf16_f32 v132, v136, v137
	v_cvt_pk_bf16_f32 v133, v138, v139
	v_add_u32_e32 v148, v241, v174
	v_cvt_pk_bf16_f32 v134, v134, v135
	v_cvt_pk_bf16_f32 v135, v146, v147
	global_store_dwordx4 v148, v[132:135], s[4:5]
	v_lshlrev_b32_e32 v136, 16, v132
	v_and_b32_e32 v137, 0xffff0000, v132
	v_lshlrev_b32_e32 v132, 16, v133
	v_and_b32_e32 v133, 0xffff0000, v133
	v_mul_f32_e32 v146, v137, v137
	v_mul_f32_e32 v147, v133, v133
	v_lshlrev_b32_e32 v138, 16, v134
	v_and_b32_e32 v139, 0xffff0000, v134
	v_lshlrev_b32_e32 v134, 16, v135
	v_and_b32_e32 v135, 0xffff0000, v135
	v_fmac_f32_e32 v146, v136, v136
	v_fmac_f32_e32 v147, v132, v132
	v_add_f32_e32 v146, v146, v147
	v_mul_f32_e32 v147, v139, v139
	v_mul_f32_e32 v149, v135, v135
	v_fmac_f32_e32 v147, v138, v138
	v_fmac_f32_e32 v149, v134, v134
	v_add_f32_e32 v147, v147, v149
	v_add_f32_e32 v149, v146, v147
	v_pk_mul_f32 v[146:147], v[186:187], v[132:133]
	v_pk_mul_f32 v[132:133], v[184:185], v[136:137]
	v_pk_mul_f32 v[136:137], v[182:183], v[134:135]
	v_pk_mul_f32 v[134:135], v[180:181], v[138:139]
	v_cvt_pk_bf16_f32 v132, v132, v133
	v_cvt_pk_bf16_f32 v133, v146, v147
	v_lshlrev_b32_e32 v146, 12, v145
	v_cvt_pk_bf16_f32 v134, v134, v135
	v_cvt_pk_bf16_f32 v135, v136, v137
	v_sub_u32_e32 v136, v148, v146
	global_store_dwordx4 v136, v[132:135], s[22:23] sc1
	v_lshlrev_b32_e32 v136, 16, v210
	v_and_b32_e32 v137, 0xffff0000, v210
	v_lshlrev_b32_e32 v132, 16, v208
	v_and_b32_e32 v133, 0xffff0000, v208
	v_lshlrev_b32_e32 v134, 16, v209
	v_and_b32_e32 v135, 0xffff0000, v209
	v_lshlrev_b32_e32 v138, 16, v211
	v_and_b32_e32 v139, 0xffff0000, v211
	v_pk_fma_f32 v[126:127], v[126:127], v[170:171], v[134:135]
	v_pk_fma_f32 v[124:125], v[124:125], v[168:169], v[132:133]
	v_pk_fma_f32 v[132:133], v[122:123], v[162:163], v[138:139]
	v_pk_fma_f32 v[122:123], v[120:121], v[160:161], v[136:137]
	v_cvt_pk_bf16_f32 v120, v124, v125
	v_cvt_pk_bf16_f32 v121, v126, v127
	v_add_u32_e32 v134, v144, v174
	v_cvt_pk_bf16_f32 v122, v122, v123
	v_cvt_pk_bf16_f32 v123, v132, v133
	global_store_dwordx4 v134, v[120:123], s[4:5]
	v_lshlrev_b32_e32 v124, 16, v120
	v_and_b32_e32 v125, 0xffff0000, v120
	v_lshlrev_b32_e32 v120, 16, v121
	v_and_b32_e32 v121, 0xffff0000, v121
	v_mul_f32_e32 v132, v125, v125
	v_mul_f32_e32 v133, v121, v121
	v_lshlrev_b32_e32 v126, 16, v122
	v_and_b32_e32 v127, 0xffff0000, v122
	v_lshlrev_b32_e32 v122, 16, v123
	v_and_b32_e32 v123, 0xffff0000, v123
	v_fmac_f32_e32 v132, v124, v124
	v_fmac_f32_e32 v133, v120, v120
	v_add_f32_e32 v132, v132, v133
	v_mul_f32_e32 v133, v127, v127
	v_mul_f32_e32 v135, v123, v123
	v_fmac_f32_e32 v133, v126, v126
	v_fmac_f32_e32 v135, v122, v122
	v_add_f32_e32 v133, v133, v135
	v_add_f32_e32 v132, v132, v133
	v_add_f32_e32 v135, v149, v132
	v_pk_mul_f32 v[132:133], v[158:159], v[120:121]
	v_pk_mul_f32 v[120:121], v[156:157], v[124:125]
	v_pk_mul_f32 v[124:125], v[154:155], v[122:123]
	v_pk_mul_f32 v[122:123], v[152:153], v[126:127]
	ds_swizzle_b32 v126, v135 offset:swizzle(SWAP,16)
	v_cvt_pk_bf16_f32 v120, v120, v121
	v_cvt_pk_bf16_f32 v121, v132, v133
	v_cvt_pk_bf16_f32 v122, v122, v123
	v_cvt_pk_bf16_f32 v123, v124, v125
	v_sub_u32_e32 v124, v134, v146
	global_store_dwordx4 v124, v[120:123], s[22:23] sc1
	s_waitcnt lgkmcnt(0)
	s_nop 0
	v_add_f32_e32 v120, v135, v126
	v_mov_b32_e32 v121, v120
	s_nop 1
	v_permlane32_swap_b32_e32 v120, v121
	s_and_saveexec_b64 s[88:89], vcc
	s_cbranch_execz .LBB0_602
	v_add_f32_e32 v120, v120, v121
	s_mov_b32 s2, 0x47800000
	v_fma_f32 v120, v120, s2, 0.5
	v_trunc_f32_e32 v120, v120
	v_mul_f32_e32 v121, 0x2f800000, v120
	v_floor_f32_e32 v121, v121
	v_fmac_f32_e32 v120, 0xcf800000, v121
	v_cvt_u32_f32_e32 v120, v120
	v_cvt_u32_f32_e32 v121, v121
	v_lshlrev_b32_e32 v122, 3, v145
	global_atomic_add_x2 v122, v[120:121], s[6:7]
.LBB0_602:
	s_or_b64 exec, exec, s[88:89]
	v_or_b32_e32 v120, 32, v242
	v_lshlrev_b32_e32 v121, 13, v120
	v_lshlrev_b32_e32 v122, 16, v204
	v_and_b32_e32 v123, 0xffff0000, v204
	v_lshlrev_b32_e32 v124, 16, v205
	v_and_b32_e32 v125, 0xffff0000, v205
	v_lshlrev_b32_e32 v126, 16, v206
	v_and_b32_e32 v127, 0xffff0000, v206
	v_lshlrev_b32_e32 v132, 16, v207
	v_and_b32_e32 v133, 0xffff0000, v207
	v_pk_fma_f32 v[114:115], v[114:115], v[198:199], v[124:125]
	v_pk_fma_f32 v[112:113], v[112:113], v[196:197], v[122:123]
	v_pk_fma_f32 v[122:123], v[106:107], v[190:191], v[132:133]
	v_pk_fma_f32 v[106:107], v[104:105], v[188:189], v[126:127]
	v_cvt_pk_bf16_f32 v104, v112, v113
	v_cvt_pk_bf16_f32 v105, v114, v115
	v_add_u32_e32 v124, v241, v121
	v_cvt_pk_bf16_f32 v106, v106, v107
	v_cvt_pk_bf16_f32 v107, v122, v123
	global_store_dwordx4 v124, v[104:107], s[4:5]
	v_lshlrev_b32_e32 v112, 16, v104
	v_and_b32_e32 v113, 0xffff0000, v104
	v_lshlrev_b32_e32 v104, 16, v105
	v_and_b32_e32 v105, 0xffff0000, v105
	v_mul_f32_e32 v122, v113, v113
	v_mul_f32_e32 v123, v105, v105
	v_lshlrev_b32_e32 v114, 16, v106
	v_and_b32_e32 v115, 0xffff0000, v106
	v_lshlrev_b32_e32 v106, 16, v107
	v_and_b32_e32 v107, 0xffff0000, v107
	v_fmac_f32_e32 v122, v112, v112
	v_fmac_f32_e32 v123, v104, v104
	v_add_f32_e32 v122, v122, v123
	v_mul_f32_e32 v123, v115, v115
	v_mul_f32_e32 v125, v107, v107
	v_fmac_f32_e32 v123, v114, v114
	v_fmac_f32_e32 v125, v106, v106
	v_add_f32_e32 v123, v123, v125
	v_add_f32_e32 v125, v122, v123
	v_pk_mul_f32 v[122:123], v[186:187], v[104:105]
	v_pk_mul_f32 v[104:105], v[184:185], v[112:113]
	v_pk_mul_f32 v[112:113], v[182:183], v[106:107]
	v_pk_mul_f32 v[106:107], v[180:181], v[114:115]
	v_cvt_pk_bf16_f32 v104, v104, v105
	v_cvt_pk_bf16_f32 v105, v122, v123
	v_lshlrev_b32_e32 v122, 12, v120
	v_cvt_pk_bf16_f32 v106, v106, v107
	v_cvt_pk_bf16_f32 v107, v112, v113
	v_sub_u32_e32 v112, v124, v122
	global_store_dwordx4 v112, v[104:107], s[22:23] sc1
	v_lshlrev_b32_e32 v112, 16, v202
	v_and_b32_e32 v113, 0xffff0000, v202
	v_lshlrev_b32_e32 v104, 16, v200
	v_and_b32_e32 v105, 0xffff0000, v200
	v_lshlrev_b32_e32 v106, 16, v201
	v_and_b32_e32 v107, 0xffff0000, v201
	v_lshlrev_b32_e32 v114, 16, v203
	v_and_b32_e32 v115, 0xffff0000, v203
	v_pk_fma_f32 v[102:103], v[102:103], v[170:171], v[106:107]
	v_pk_fma_f32 v[100:101], v[100:101], v[168:169], v[104:105]
	v_pk_fma_f32 v[104:105], v[94:95], v[162:163], v[114:115]
	v_pk_fma_f32 v[94:95], v[92:93], v[160:161], v[112:113]
	v_cvt_pk_bf16_f32 v92, v100, v101
	v_cvt_pk_bf16_f32 v93, v102, v103
	v_add_u32_e32 v106, v144, v121
	v_cvt_pk_bf16_f32 v94, v94, v95
	v_cvt_pk_bf16_f32 v95, v104, v105
	global_store_dwordx4 v106, v[92:95], s[4:5]
	v_lshlrev_b32_e32 v100, 16, v92
	v_and_b32_e32 v101, 0xffff0000, v92
	v_lshlrev_b32_e32 v92, 16, v93
	v_and_b32_e32 v93, 0xffff0000, v93
	v_mul_f32_e32 v104, v101, v101
	v_mul_f32_e32 v105, v93, v93
	v_lshlrev_b32_e32 v102, 16, v94
	v_and_b32_e32 v103, 0xffff0000, v94
	v_lshlrev_b32_e32 v94, 16, v95
	v_and_b32_e32 v95, 0xffff0000, v95
	v_fmac_f32_e32 v104, v100, v100
	v_fmac_f32_e32 v105, v92, v92
	v_add_f32_e32 v104, v104, v105
	v_mul_f32_e32 v105, v103, v103
	v_mul_f32_e32 v107, v95, v95
	v_fmac_f32_e32 v105, v102, v102
	v_fmac_f32_e32 v107, v94, v94
	v_add_f32_e32 v105, v105, v107
	v_add_f32_e32 v104, v104, v105
	v_add_f32_e32 v107, v125, v104
	v_pk_mul_f32 v[104:105], v[158:159], v[92:93]
	v_pk_mul_f32 v[92:93], v[156:157], v[100:101]
	v_pk_mul_f32 v[100:101], v[154:155], v[94:95]
	v_pk_mul_f32 v[94:95], v[152:153], v[102:103]
	ds_swizzle_b32 v102, v107 offset:swizzle(SWAP,16)
	v_cvt_pk_bf16_f32 v92, v92, v93
	v_cvt_pk_bf16_f32 v93, v104, v105
	v_cvt_pk_bf16_f32 v94, v94, v95
	v_cvt_pk_bf16_f32 v95, v100, v101
	v_sub_u32_e32 v100, v106, v122
	global_store_dwordx4 v100, v[92:95], s[22:23] sc1
	s_waitcnt lgkmcnt(0)
	s_nop 0
	v_add_f32_e32 v92, v107, v102
	v_mov_b32_e32 v93, v92
	s_nop 1
	v_permlane32_swap_b32_e32 v92, v93
	s_and_saveexec_b64 s[88:89], vcc
	s_cbranch_execz .LBB0_604
	v_add_f32_e32 v92, v92, v93
	s_mov_b32 s2, 0x47800000
	v_fma_f32 v92, v92, s2, 0.5
	v_trunc_f32_e32 v92, v92
	v_mul_f32_e32 v93, 0x2f800000, v92
	v_floor_f32_e32 v93, v93
	v_fmac_f32_e32 v92, 0xcf800000, v93
	v_cvt_u32_f32_e32 v92, v92
	v_cvt_u32_f32_e32 v93, v93
	v_lshlrev_b32_e32 v94, 3, v120
	global_atomic_add_x2 v94, v[92:93], s[6:7]
.LBB0_604:
	s_or_b64 exec, exec, s[88:89]
	v_or_b32_e32 v92, 48, v242
	v_lshlrev_b32_e32 v93, 13, v92
	v_lshlrev_b32_e32 v94, 16, v192
	v_and_b32_e32 v95, 0xffff0000, v192
	v_lshlrev_b32_e32 v100, 16, v193
	v_and_b32_e32 v101, 0xffff0000, v193
	v_lshlrev_b32_e32 v102, 16, v194
	v_and_b32_e32 v103, 0xffff0000, v194
	v_lshlrev_b32_e32 v104, 16, v195
	v_and_b32_e32 v105, 0xffff0000, v195
	v_pk_fma_f32 v[86:87], v[86:87], v[198:199], v[100:101]
	v_pk_fma_f32 v[84:85], v[84:85], v[196:197], v[94:95]
	v_pk_fma_f32 v[94:95], v[82:83], v[190:191], v[104:105]
	v_pk_fma_f32 v[82:83], v[80:81], v[188:189], v[102:103]
	v_cvt_pk_bf16_f32 v80, v84, v85
	v_cvt_pk_bf16_f32 v81, v86, v87
	v_add_u32_e32 v100, v241, v93
	v_cvt_pk_bf16_f32 v82, v82, v83
	v_cvt_pk_bf16_f32 v83, v94, v95
	global_store_dwordx4 v100, v[80:83], s[4:5]
	v_lshlrev_b32_e32 v84, 16, v80
	v_and_b32_e32 v85, 0xffff0000, v80
	v_lshlrev_b32_e32 v80, 16, v81
	v_and_b32_e32 v81, 0xffff0000, v81
	v_mul_f32_e32 v94, v85, v85
	v_mul_f32_e32 v95, v81, v81
	v_lshlrev_b32_e32 v86, 16, v82
	v_and_b32_e32 v87, 0xffff0000, v82
	v_lshlrev_b32_e32 v82, 16, v83
	v_and_b32_e32 v83, 0xffff0000, v83
	v_fmac_f32_e32 v94, v84, v84
	v_fmac_f32_e32 v95, v80, v80
	v_add_f32_e32 v94, v94, v95
	v_mul_f32_e32 v95, v87, v87
	v_mul_f32_e32 v101, v83, v83
	v_fmac_f32_e32 v95, v86, v86
	v_fmac_f32_e32 v101, v82, v82
	v_add_f32_e32 v95, v95, v101
	v_add_f32_e32 v101, v94, v95
	v_pk_mul_f32 v[94:95], v[186:187], v[80:81]
	v_pk_mul_f32 v[80:81], v[184:185], v[84:85]
	v_pk_mul_f32 v[84:85], v[182:183], v[82:83]
	v_pk_mul_f32 v[82:83], v[180:181], v[86:87]
	v_cvt_pk_bf16_f32 v80, v80, v81
	v_cvt_pk_bf16_f32 v81, v94, v95
	v_lshlrev_b32_e32 v94, 12, v92
	v_cvt_pk_bf16_f32 v82, v82, v83
	v_cvt_pk_bf16_f32 v83, v84, v85
	v_sub_u32_e32 v84, v100, v94
	global_store_dwordx4 v84, v[80:83], s[22:23] sc1
	v_lshlrev_b32_e32 v84, 16, v166
	v_and_b32_e32 v85, 0xffff0000, v166
	v_lshlrev_b32_e32 v80, 16, v164
	v_and_b32_e32 v81, 0xffff0000, v164
	v_lshlrev_b32_e32 v82, 16, v165
	v_and_b32_e32 v83, 0xffff0000, v165
	v_lshlrev_b32_e32 v86, 16, v167
	v_and_b32_e32 v87, 0xffff0000, v167
	v_pk_fma_f32 v[78:79], v[78:79], v[170:171], v[82:83]
	v_pk_fma_f32 v[76:77], v[76:77], v[168:169], v[80:81]
	v_pk_fma_f32 v[80:81], v[70:71], v[162:163], v[86:87]
	v_pk_fma_f32 v[70:71], v[68:69], v[160:161], v[84:85]
	v_cvt_pk_bf16_f32 v68, v76, v77
	v_cvt_pk_bf16_f32 v69, v78, v79
	v_add_u32_e32 v82, v144, v93
	v_cvt_pk_bf16_f32 v70, v70, v71
	v_cvt_pk_bf16_f32 v71, v80, v81
	global_store_dwordx4 v82, v[68:71], s[4:5]
	v_lshlrev_b32_e32 v76, 16, v68
	v_and_b32_e32 v77, 0xffff0000, v68
	v_lshlrev_b32_e32 v68, 16, v69
	v_and_b32_e32 v69, 0xffff0000, v69
	v_mul_f32_e32 v80, v77, v77
	v_mul_f32_e32 v81, v69, v69
	v_lshlrev_b32_e32 v78, 16, v70
	v_and_b32_e32 v79, 0xffff0000, v70
	v_lshlrev_b32_e32 v70, 16, v71
	v_and_b32_e32 v71, 0xffff0000, v71
	v_fmac_f32_e32 v80, v76, v76
	v_fmac_f32_e32 v81, v68, v68
	v_add_f32_e32 v80, v80, v81
	v_mul_f32_e32 v81, v79, v79
	v_mul_f32_e32 v83, v71, v71
	v_fmac_f32_e32 v81, v78, v78
	v_fmac_f32_e32 v83, v70, v70
	v_add_f32_e32 v81, v81, v83
	v_add_f32_e32 v80, v80, v81
	v_add_f32_e32 v83, v101, v80
	v_pk_mul_f32 v[80:81], v[158:159], v[68:69]
	v_pk_mul_f32 v[68:69], v[156:157], v[76:77]
	v_pk_mul_f32 v[76:77], v[154:155], v[70:71]
	v_pk_mul_f32 v[70:71], v[152:153], v[78:79]
	ds_swizzle_b32 v78, v83 offset:swizzle(SWAP,16)
	v_cvt_pk_bf16_f32 v68, v68, v69
	v_cvt_pk_bf16_f32 v69, v80, v81
	v_cvt_pk_bf16_f32 v70, v70, v71
	v_cvt_pk_bf16_f32 v71, v76, v77
	v_sub_u32_e32 v76, v82, v94
	global_store_dwordx4 v76, v[68:71], s[22:23] sc1
	s_waitcnt lgkmcnt(0)
	s_nop 0
	v_add_f32_e32 v68, v83, v78
	v_mov_b32_e32 v69, v68
	s_nop 1
	v_permlane32_swap_b32_e32 v68, v69
	s_and_saveexec_b64 s[88:89], vcc
	s_cbranch_execz .LBB0_606
	v_add_f32_e32 v68, v68, v69
	s_mov_b32 s2, 0x47800000
	v_fma_f32 v68, v68, s2, 0.5
	v_trunc_f32_e32 v68, v68
	v_mul_f32_e32 v69, 0x2f800000, v68
	v_floor_f32_e32 v69, v69
	v_fmac_f32_e32 v68, 0xcf800000, v69
	v_cvt_u32_f32_e32 v68, v68
	v_cvt_u32_f32_e32 v69, v69
	v_lshlrev_b32_e32 v70, 3, v92
	global_atomic_add_x2 v70, v[68:69], s[6:7]
.LBB0_606:
	s_or_b64 exec, exec, s[88:89]
	v_add_u32_e32 v120, 0x80, v242
	v_lshlrev_b32_e32 v121, 13, v120
	v_lshlrev_b32_e32 v122, 16, v140
	v_and_b32_e32 v123, 0xffff0000, v140
	v_lshlrev_b32_e32 v124, 16, v141
	v_and_b32_e32 v125, 0xffff0000, v141
	v_lshlrev_b32_e32 v126, 16, v142
	v_and_b32_e32 v127, 0xffff0000, v142
	v_lshlrev_b32_e32 v132, 16, v143
	v_and_b32_e32 v133, 0xffff0000, v143
	ds_read_b128 v[112:115], v243 offset:2048
	ds_read_b128 v[104:107], v243 offset:2064
	ds_read_b128 v[100:103], v243 offset:6144
	ds_read_b128 v[92:95], v243 offset:6160
	ds_read_b128 v[84:87], v243 offset:2560
	ds_read_b128 v[80:83], v243 offset:2576
	ds_read_b128 v[76:79], v243 offset:6656
	ds_read_b128 v[68:71], v243 offset:6672
	s_waitcnt lgkmcnt(7)
	v_pk_fma_f32 v[62:63], v[62:63], v[114:115], v[124:125]
	v_pk_fma_f32 v[60:61], v[60:61], v[112:113], v[122:123]
	s_waitcnt lgkmcnt(6)
	v_pk_fma_f32 v[122:123], v[58:59], v[106:107], v[132:133]
	v_pk_fma_f32 v[58:59], v[56:57], v[104:105], v[126:127]
	v_cvt_pk_bf16_f32 v56, v60, v61
	v_cvt_pk_bf16_f32 v57, v62, v63
	v_add_u32_e32 v124, v241, v121
	v_cvt_pk_bf16_f32 v58, v58, v59
	v_cvt_pk_bf16_f32 v59, v122, v123
	global_store_dwordx4 v124, v[56:59], s[4:5]
	v_lshlrev_b32_e32 v60, 16, v56
	v_and_b32_e32 v61, 0xffff0000, v56
	v_lshlrev_b32_e32 v56, 16, v57
	v_and_b32_e32 v57, 0xffff0000, v57
	v_mul_f32_e32 v122, v61, v61
	v_mul_f32_e32 v123, v57, v57
	v_lshlrev_b32_e32 v62, 16, v58
	v_and_b32_e32 v63, 0xffff0000, v58
	v_lshlrev_b32_e32 v58, 16, v59
	v_and_b32_e32 v59, 0xffff0000, v59
	v_fmac_f32_e32 v122, v60, v60
	v_fmac_f32_e32 v123, v56, v56
	v_add_f32_e32 v122, v122, v123
	v_mul_f32_e32 v123, v63, v63
	v_mul_f32_e32 v125, v59, v59
	v_fmac_f32_e32 v123, v62, v62
	v_fmac_f32_e32 v125, v58, v58
	v_add_f32_e32 v123, v123, v125
	v_add_f32_e32 v125, v122, v123
	s_waitcnt lgkmcnt(5)
	v_pk_mul_f32 v[122:123], v[102:103], v[56:57]
	v_pk_mul_f32 v[56:57], v[100:101], v[60:61]
	s_waitcnt lgkmcnt(4)
	v_pk_mul_f32 v[60:61], v[94:95], v[58:59]
	v_pk_mul_f32 v[58:59], v[92:93], v[62:63]
	v_cvt_pk_bf16_f32 v56, v56, v57
	v_cvt_pk_bf16_f32 v57, v122, v123
	v_lshlrev_b32_e32 v122, 12, v120
	v_cvt_pk_bf16_f32 v58, v58, v59
	v_cvt_pk_bf16_f32 v59, v60, v61
	v_sub_u32_e32 v60, v124, v122
	global_store_dwordx4 v60, v[56:59], s[22:23] sc1
	v_lshlrev_b32_e32 v60, 16, v130
	v_and_b32_e32 v61, 0xffff0000, v130
	v_lshlrev_b32_e32 v56, 16, v128
	v_and_b32_e32 v57, 0xffff0000, v128
	v_lshlrev_b32_e32 v58, 16, v129
	v_and_b32_e32 v59, 0xffff0000, v129
	v_lshlrev_b32_e32 v62, 16, v131
	v_and_b32_e32 v63, 0xffff0000, v131
	s_waitcnt lgkmcnt(3)
	v_pk_fma_f32 v[54:55], v[54:55], v[86:87], v[58:59]
	v_pk_fma_f32 v[52:53], v[52:53], v[84:85], v[56:57]
	s_waitcnt lgkmcnt(2)
	v_pk_fma_f32 v[56:57], v[50:51], v[82:83], v[62:63]
	v_pk_fma_f32 v[50:51], v[48:49], v[80:81], v[60:61]
	v_cvt_pk_bf16_f32 v48, v52, v53
	v_cvt_pk_bf16_f32 v49, v54, v55
	v_add_u32_e32 v58, v144, v121
	v_cvt_pk_bf16_f32 v50, v50, v51
	v_cvt_pk_bf16_f32 v51, v56, v57
	global_store_dwordx4 v58, v[48:51], s[4:5]
	v_lshlrev_b32_e32 v52, 16, v48
	v_and_b32_e32 v53, 0xffff0000, v48
	v_lshlrev_b32_e32 v48, 16, v49
	v_and_b32_e32 v49, 0xffff0000, v49
	v_mul_f32_e32 v56, v53, v53
	v_mul_f32_e32 v57, v49, v49
	v_lshlrev_b32_e32 v54, 16, v50
	v_and_b32_e32 v55, 0xffff0000, v50
	v_lshlrev_b32_e32 v50, 16, v51
	v_and_b32_e32 v51, 0xffff0000, v51
	v_fmac_f32_e32 v56, v52, v52
	v_fmac_f32_e32 v57, v48, v48
	v_add_f32_e32 v56, v56, v57
	v_mul_f32_e32 v57, v55, v55
	v_mul_f32_e32 v59, v51, v51
	v_fmac_f32_e32 v57, v54, v54
	v_fmac_f32_e32 v59, v50, v50
	v_add_f32_e32 v57, v57, v59
	v_add_f32_e32 v56, v56, v57
	v_add_f32_e32 v59, v125, v56
	s_waitcnt lgkmcnt(1)
	v_pk_mul_f32 v[56:57], v[78:79], v[48:49]
	v_pk_mul_f32 v[48:49], v[76:77], v[52:53]
	s_waitcnt lgkmcnt(0)
	v_pk_mul_f32 v[52:53], v[70:71], v[50:51]
	v_pk_mul_f32 v[50:51], v[68:69], v[54:55]
	ds_swizzle_b32 v54, v59 offset:swizzle(SWAP,16)
	v_cvt_pk_bf16_f32 v48, v48, v49
	v_cvt_pk_bf16_f32 v49, v56, v57
	v_cvt_pk_bf16_f32 v50, v50, v51
	v_cvt_pk_bf16_f32 v51, v52, v53
	v_sub_u32_e32 v52, v58, v122
	global_store_dwordx4 v52, v[48:51], s[22:23] sc1
	s_waitcnt lgkmcnt(0)
	s_nop 0
	v_add_f32_e32 v48, v59, v54
	v_mov_b32_e32 v49, v48
	s_nop 1
	v_permlane32_swap_b32_e32 v48, v49
	s_and_saveexec_b64 s[88:89], vcc
	s_cbranch_execz .LBB0_608
	v_add_f32_e32 v48, v48, v49
	s_mov_b32 s2, 0x47800000
	v_fma_f32 v48, v48, s2, 0.5
	v_trunc_f32_e32 v48, v48
	v_mul_f32_e32 v49, 0x2f800000, v48
	v_floor_f32_e32 v49, v49
	v_fmac_f32_e32 v48, 0xcf800000, v49
	v_cvt_u32_f32_e32 v48, v48
	v_cvt_u32_f32_e32 v49, v49
	v_lshlrev_b32_e32 v50, 3, v120
	global_atomic_add_x2 v50, v[48:49], s[6:7]
.LBB0_608:
	s_or_b64 exec, exec, s[88:89]
	v_add_u32_e32 v48, 0x90, v242
	v_lshlrev_b32_e32 v49, 13, v48
	v_lshlrev_b32_e32 v50, 16, v116
	v_and_b32_e32 v51, 0xffff0000, v116
	v_lshlrev_b32_e32 v52, 16, v117
	v_and_b32_e32 v53, 0xffff0000, v117
	v_lshlrev_b32_e32 v54, 16, v118
	v_and_b32_e32 v55, 0xffff0000, v118
	v_lshlrev_b32_e32 v56, 16, v119
	v_and_b32_e32 v57, 0xffff0000, v119
	v_pk_fma_f32 v[46:47], v[46:47], v[114:115], v[52:53]
	v_pk_fma_f32 v[44:45], v[44:45], v[112:113], v[50:51]
	v_pk_fma_f32 v[50:51], v[42:43], v[106:107], v[56:57]
	v_pk_fma_f32 v[42:43], v[40:41], v[104:105], v[54:55]
	v_cvt_pk_bf16_f32 v40, v44, v45
	v_cvt_pk_bf16_f32 v41, v46, v47
	v_add_u32_e32 v52, v241, v49
	v_cvt_pk_bf16_f32 v42, v42, v43
	v_cvt_pk_bf16_f32 v43, v50, v51
	global_store_dwordx4 v52, v[40:43], s[4:5]
	v_lshlrev_b32_e32 v44, 16, v40
	v_and_b32_e32 v45, 0xffff0000, v40
	v_lshlrev_b32_e32 v40, 16, v41
	v_and_b32_e32 v41, 0xffff0000, v41
	v_mul_f32_e32 v50, v45, v45
	v_mul_f32_e32 v51, v41, v41
	v_lshlrev_b32_e32 v46, 16, v42
	v_and_b32_e32 v47, 0xffff0000, v42
	v_lshlrev_b32_e32 v42, 16, v43
	v_and_b32_e32 v43, 0xffff0000, v43
	v_fmac_f32_e32 v50, v44, v44
	v_fmac_f32_e32 v51, v40, v40
	v_add_f32_e32 v50, v50, v51
	v_mul_f32_e32 v51, v47, v47
	v_mul_f32_e32 v53, v43, v43
	v_fmac_f32_e32 v51, v46, v46
	v_fmac_f32_e32 v53, v42, v42
	v_add_f32_e32 v51, v51, v53
	v_add_f32_e32 v53, v50, v51
	v_pk_mul_f32 v[50:51], v[102:103], v[40:41]
	v_pk_mul_f32 v[40:41], v[100:101], v[44:45]
	v_pk_mul_f32 v[44:45], v[94:95], v[42:43]
	v_pk_mul_f32 v[42:43], v[92:93], v[46:47]
	v_cvt_pk_bf16_f32 v40, v40, v41
	v_cvt_pk_bf16_f32 v41, v50, v51
	v_lshlrev_b32_e32 v50, 12, v48
	v_cvt_pk_bf16_f32 v42, v42, v43
	v_cvt_pk_bf16_f32 v43, v44, v45
	v_sub_u32_e32 v44, v52, v50
	global_store_dwordx4 v44, v[40:43], s[22:23] sc1
	v_lshlrev_b32_e32 v44, 16, v110
	v_and_b32_e32 v45, 0xffff0000, v110
	v_lshlrev_b32_e32 v40, 16, v108
	v_and_b32_e32 v41, 0xffff0000, v108
	v_lshlrev_b32_e32 v42, 16, v109
	v_and_b32_e32 v43, 0xffff0000, v109
	v_lshlrev_b32_e32 v46, 16, v111
	v_and_b32_e32 v47, 0xffff0000, v111
	v_pk_fma_f32 v[38:39], v[38:39], v[86:87], v[42:43]
	v_pk_fma_f32 v[36:37], v[36:37], v[84:85], v[40:41]
	v_pk_fma_f32 v[40:41], v[34:35], v[82:83], v[46:47]
	v_pk_fma_f32 v[34:35], v[32:33], v[80:81], v[44:45]
	v_cvt_pk_bf16_f32 v32, v36, v37
	v_cvt_pk_bf16_f32 v33, v38, v39
	v_add_u32_e32 v42, v144, v49
	v_cvt_pk_bf16_f32 v34, v34, v35
	v_cvt_pk_bf16_f32 v35, v40, v41
	global_store_dwordx4 v42, v[32:35], s[4:5]
	v_lshlrev_b32_e32 v36, 16, v32
	v_and_b32_e32 v37, 0xffff0000, v32
	v_lshlrev_b32_e32 v32, 16, v33
	v_and_b32_e32 v33, 0xffff0000, v33
	v_mul_f32_e32 v40, v37, v37
	v_mul_f32_e32 v41, v33, v33
	v_lshlrev_b32_e32 v38, 16, v34
	v_and_b32_e32 v39, 0xffff0000, v34
	v_lshlrev_b32_e32 v34, 16, v35
	v_and_b32_e32 v35, 0xffff0000, v35
	v_fmac_f32_e32 v40, v36, v36
	v_fmac_f32_e32 v41, v32, v32
	v_add_f32_e32 v40, v40, v41
	v_mul_f32_e32 v41, v39, v39
	v_mul_f32_e32 v43, v35, v35
	v_fmac_f32_e32 v41, v38, v38
	v_fmac_f32_e32 v43, v34, v34
	v_add_f32_e32 v41, v41, v43
	v_add_f32_e32 v40, v40, v41
	v_add_f32_e32 v43, v53, v40
	v_pk_mul_f32 v[40:41], v[78:79], v[32:33]
	v_pk_mul_f32 v[32:33], v[76:77], v[36:37]
	v_pk_mul_f32 v[36:37], v[70:71], v[34:35]
	v_pk_mul_f32 v[34:35], v[68:69], v[38:39]
	ds_swizzle_b32 v38, v43 offset:swizzle(SWAP,16)
	v_cvt_pk_bf16_f32 v32, v32, v33
	v_cvt_pk_bf16_f32 v33, v40, v41
	v_cvt_pk_bf16_f32 v34, v34, v35
	v_cvt_pk_bf16_f32 v35, v36, v37
	v_sub_u32_e32 v36, v42, v50
	global_store_dwordx4 v36, v[32:35], s[22:23] sc1
	s_waitcnt lgkmcnt(0)
	s_nop 0
	v_add_f32_e32 v32, v43, v38
	v_mov_b32_e32 v33, v32
	s_nop 1
	v_permlane32_swap_b32_e32 v32, v33
	s_and_saveexec_b64 s[88:89], vcc
	s_cbranch_execz .LBB0_610
	v_add_f32_e32 v32, v32, v33
	s_mov_b32 s2, 0x47800000
	v_fma_f32 v32, v32, s2, 0.5
	v_trunc_f32_e32 v32, v32
	v_mul_f32_e32 v33, 0x2f800000, v32
	v_floor_f32_e32 v33, v33
	v_fmac_f32_e32 v32, 0xcf800000, v33
	v_cvt_u32_f32_e32 v32, v32
	v_cvt_u32_f32_e32 v33, v33
	v_lshlrev_b32_e32 v34, 3, v48
	global_atomic_add_x2 v34, v[32:33], s[6:7]
.LBB0_610:
	s_or_b64 exec, exec, s[88:89]
	v_add_u32_e32 v32, 0xa0, v242
	v_lshlrev_b32_e32 v33, 13, v32
	v_lshlrev_b32_e32 v34, 16, v96
	v_and_b32_e32 v35, 0xffff0000, v96
	v_lshlrev_b32_e32 v36, 16, v97
	v_and_b32_e32 v37, 0xffff0000, v97
	v_lshlrev_b32_e32 v38, 16, v98
	v_and_b32_e32 v39, 0xffff0000, v98
	v_lshlrev_b32_e32 v40, 16, v99
	v_and_b32_e32 v41, 0xffff0000, v99
	v_pk_fma_f32 v[30:31], v[30:31], v[114:115], v[36:37]
	v_pk_fma_f32 v[28:29], v[28:29], v[112:113], v[34:35]
	v_pk_fma_f32 v[34:35], v[26:27], v[106:107], v[40:41]
	v_pk_fma_f32 v[26:27], v[24:25], v[104:105], v[38:39]
	v_cvt_pk_bf16_f32 v24, v28, v29
	v_cvt_pk_bf16_f32 v25, v30, v31
	v_add_u32_e32 v36, v241, v33
	v_cvt_pk_bf16_f32 v26, v26, v27
	v_cvt_pk_bf16_f32 v27, v34, v35
	global_store_dwordx4 v36, v[24:27], s[4:5]
	v_lshlrev_b32_e32 v28, 16, v24
	v_and_b32_e32 v29, 0xffff0000, v24
	v_lshlrev_b32_e32 v24, 16, v25
	v_and_b32_e32 v25, 0xffff0000, v25
	v_mul_f32_e32 v34, v29, v29
	v_mul_f32_e32 v35, v25, v25
	v_lshlrev_b32_e32 v30, 16, v26
	v_and_b32_e32 v31, 0xffff0000, v26
	v_lshlrev_b32_e32 v26, 16, v27
	v_and_b32_e32 v27, 0xffff0000, v27
	v_fmac_f32_e32 v34, v28, v28
	v_fmac_f32_e32 v35, v24, v24
	v_add_f32_e32 v34, v34, v35
	v_mul_f32_e32 v35, v31, v31
	v_mul_f32_e32 v37, v27, v27
	v_fmac_f32_e32 v35, v30, v30
	v_fmac_f32_e32 v37, v26, v26
	v_add_f32_e32 v35, v35, v37
	v_add_f32_e32 v37, v34, v35
	v_pk_mul_f32 v[34:35], v[102:103], v[24:25]
	v_pk_mul_f32 v[24:25], v[100:101], v[28:29]
	v_pk_mul_f32 v[28:29], v[94:95], v[26:27]
	v_pk_mul_f32 v[26:27], v[92:93], v[30:31]
	v_cvt_pk_bf16_f32 v24, v24, v25
	v_cvt_pk_bf16_f32 v25, v34, v35
	v_lshlrev_b32_e32 v34, 12, v32
	v_cvt_pk_bf16_f32 v26, v26, v27
	v_cvt_pk_bf16_f32 v27, v28, v29
	v_sub_u32_e32 v28, v36, v34
	global_store_dwordx4 v28, v[24:27], s[22:23] sc1
	v_lshlrev_b32_e32 v28, 16, v90
	v_and_b32_e32 v29, 0xffff0000, v90
	v_lshlrev_b32_e32 v24, 16, v88
	v_and_b32_e32 v25, 0xffff0000, v88
	v_lshlrev_b32_e32 v26, 16, v89
	v_and_b32_e32 v27, 0xffff0000, v89
	v_lshlrev_b32_e32 v30, 16, v91
	v_and_b32_e32 v31, 0xffff0000, v91
	v_pk_fma_f32 v[22:23], v[22:23], v[86:87], v[26:27]
	v_pk_fma_f32 v[20:21], v[20:21], v[84:85], v[24:25]
	v_pk_fma_f32 v[24:25], v[18:19], v[82:83], v[30:31]
	v_pk_fma_f32 v[18:19], v[16:17], v[80:81], v[28:29]
	v_cvt_pk_bf16_f32 v16, v20, v21
	v_cvt_pk_bf16_f32 v17, v22, v23
	v_add_u32_e32 v26, v144, v33
	v_cvt_pk_bf16_f32 v18, v18, v19
	v_cvt_pk_bf16_f32 v19, v24, v25
	global_store_dwordx4 v26, v[16:19], s[4:5]
	v_lshlrev_b32_e32 v20, 16, v16
	v_and_b32_e32 v21, 0xffff0000, v16
	v_lshlrev_b32_e32 v16, 16, v17
	v_and_b32_e32 v17, 0xffff0000, v17
	v_mul_f32_e32 v24, v21, v21
	v_mul_f32_e32 v25, v17, v17
	v_lshlrev_b32_e32 v22, 16, v18
	v_and_b32_e32 v23, 0xffff0000, v18
	v_lshlrev_b32_e32 v18, 16, v19
	v_and_b32_e32 v19, 0xffff0000, v19
	v_fmac_f32_e32 v24, v20, v20
	v_fmac_f32_e32 v25, v16, v16
	v_add_f32_e32 v24, v24, v25
	v_mul_f32_e32 v25, v23, v23
	v_mul_f32_e32 v27, v19, v19
	v_fmac_f32_e32 v25, v22, v22
	v_fmac_f32_e32 v27, v18, v18
	v_add_f32_e32 v25, v25, v27
	v_add_f32_e32 v24, v24, v25
	v_add_f32_e32 v27, v37, v24
	v_pk_mul_f32 v[24:25], v[78:79], v[16:17]
	v_pk_mul_f32 v[16:17], v[76:77], v[20:21]
	v_pk_mul_f32 v[20:21], v[70:71], v[18:19]
	v_pk_mul_f32 v[18:19], v[68:69], v[22:23]
	ds_swizzle_b32 v22, v27 offset:swizzle(SWAP,16)
	v_cvt_pk_bf16_f32 v16, v16, v17
	v_cvt_pk_bf16_f32 v17, v24, v25
	v_cvt_pk_bf16_f32 v18, v18, v19
	v_cvt_pk_bf16_f32 v19, v20, v21
	v_sub_u32_e32 v20, v26, v34
	global_store_dwordx4 v20, v[16:19], s[22:23] sc1
	s_waitcnt lgkmcnt(0)
	s_nop 0
	v_add_f32_e32 v16, v27, v22
	v_mov_b32_e32 v17, v16
	s_nop 1
	v_permlane32_swap_b32_e32 v16, v17
	s_and_saveexec_b64 s[88:89], vcc
	s_cbranch_execz .LBB0_612
	v_add_f32_e32 v16, v16, v17
	s_mov_b32 s2, 0x47800000
	v_fma_f32 v16, v16, s2, 0.5
	v_trunc_f32_e32 v16, v16
	v_mul_f32_e32 v17, 0x2f800000, v16
	v_floor_f32_e32 v17, v17
	v_fmac_f32_e32 v16, 0xcf800000, v17
	v_cvt_u32_f32_e32 v16, v16
	v_cvt_u32_f32_e32 v17, v17
	v_lshlrev_b32_e32 v18, 3, v32
	global_atomic_add_x2 v18, v[16:17], s[6:7]
.LBB0_612:
	s_or_b64 exec, exec, s[88:89]
	v_add_u32_e32 v16, 0xb0, v242
	v_lshlrev_b32_e32 v17, 13, v16
	v_lshlrev_b32_e32 v18, 16, v72
	v_and_b32_e32 v19, 0xffff0000, v72
	v_lshlrev_b32_e32 v20, 16, v73
	v_and_b32_e32 v21, 0xffff0000, v73
	v_lshlrev_b32_e32 v22, 16, v74
	v_and_b32_e32 v23, 0xffff0000, v74
	v_lshlrev_b32_e32 v24, 16, v75
	v_and_b32_e32 v25, 0xffff0000, v75
	v_pk_fma_f32 v[14:15], v[14:15], v[114:115], v[20:21]
	v_pk_fma_f32 v[12:13], v[12:13], v[112:113], v[18:19]
	v_pk_fma_f32 v[18:19], v[10:11], v[106:107], v[24:25]
	v_pk_fma_f32 v[10:11], v[8:9], v[104:105], v[22:23]
	v_cvt_pk_bf16_f32 v8, v12, v13
	v_cvt_pk_bf16_f32 v9, v14, v15
	v_add_u32_e32 v20, v241, v17
	v_cvt_pk_bf16_f32 v10, v10, v11
	v_cvt_pk_bf16_f32 v11, v18, v19
	global_store_dwordx4 v20, v[8:11], s[4:5]
	v_lshlrev_b32_e32 v12, 16, v8
	v_and_b32_e32 v13, 0xffff0000, v8
	v_lshlrev_b32_e32 v8, 16, v9
	v_and_b32_e32 v9, 0xffff0000, v9
	v_mul_f32_e32 v18, v13, v13
	v_mul_f32_e32 v19, v9, v9
	v_lshlrev_b32_e32 v14, 16, v10
	v_and_b32_e32 v15, 0xffff0000, v10
	v_lshlrev_b32_e32 v10, 16, v11
	v_and_b32_e32 v11, 0xffff0000, v11
	v_fmac_f32_e32 v18, v12, v12
	v_fmac_f32_e32 v19, v8, v8
	v_add_f32_e32 v18, v18, v19
	v_mul_f32_e32 v19, v15, v15
	v_mul_f32_e32 v21, v11, v11
	v_fmac_f32_e32 v19, v14, v14
	v_fmac_f32_e32 v21, v10, v10
	v_add_f32_e32 v19, v19, v21
	v_add_f32_e32 v21, v18, v19
	v_pk_mul_f32 v[18:19], v[102:103], v[8:9]
	v_pk_mul_f32 v[8:9], v[100:101], v[12:13]
	v_pk_mul_f32 v[12:13], v[94:95], v[10:11]
	v_pk_mul_f32 v[10:11], v[92:93], v[14:15]
	v_cvt_pk_bf16_f32 v8, v8, v9
	v_cvt_pk_bf16_f32 v9, v18, v19
	v_lshlrev_b32_e32 v18, 12, v16
	v_cvt_pk_bf16_f32 v10, v10, v11
	v_cvt_pk_bf16_f32 v11, v12, v13
	v_sub_u32_e32 v12, v20, v18
	global_store_dwordx4 v12, v[8:11], s[22:23] sc1
	v_lshlrev_b32_e32 v12, 16, v66
	v_and_b32_e32 v13, 0xffff0000, v66
	v_lshlrev_b32_e32 v8, 16, v64
	v_and_b32_e32 v9, 0xffff0000, v64
	v_lshlrev_b32_e32 v10, 16, v65
	v_and_b32_e32 v11, 0xffff0000, v65
	v_lshlrev_b32_e32 v14, 16, v67
	v_and_b32_e32 v15, 0xffff0000, v67
	v_pk_fma_f32 v[6:7], v[6:7], v[86:87], v[10:11]
	v_pk_fma_f32 v[4:5], v[4:5], v[84:85], v[8:9]
	v_pk_fma_f32 v[8:9], v[2:3], v[82:83], v[14:15]
	v_pk_fma_f32 v[2:3], v[0:1], v[80:81], v[12:13]
	v_cvt_pk_bf16_f32 v0, v4, v5
	v_cvt_pk_bf16_f32 v1, v6, v7
	v_add_u32_e32 v10, v144, v17
	v_cvt_pk_bf16_f32 v2, v2, v3
	v_cvt_pk_bf16_f32 v3, v8, v9
	global_store_dwordx4 v10, v[0:3], s[4:5]
	v_lshlrev_b32_e32 v4, 16, v0
	v_and_b32_e32 v5, 0xffff0000, v0
	v_lshlrev_b32_e32 v0, 16, v1
	v_and_b32_e32 v1, 0xffff0000, v1
	v_mul_f32_e32 v8, v5, v5
	v_mul_f32_e32 v9, v1, v1
	v_lshlrev_b32_e32 v6, 16, v2
	v_and_b32_e32 v7, 0xffff0000, v2
	v_lshlrev_b32_e32 v2, 16, v3
	v_and_b32_e32 v3, 0xffff0000, v3
	v_fmac_f32_e32 v8, v4, v4
	v_fmac_f32_e32 v9, v0, v0
	v_add_f32_e32 v8, v8, v9
	v_mul_f32_e32 v9, v7, v7
	v_mul_f32_e32 v11, v3, v3
	v_fmac_f32_e32 v9, v6, v6
	v_fmac_f32_e32 v11, v2, v2
	v_add_f32_e32 v9, v9, v11
	v_add_f32_e32 v8, v8, v9
	v_add_f32_e32 v11, v21, v8
	v_pk_mul_f32 v[8:9], v[78:79], v[0:1]
	v_pk_mul_f32 v[0:1], v[76:77], v[4:5]
	v_pk_mul_f32 v[4:5], v[70:71], v[2:3]
	v_pk_mul_f32 v[2:3], v[68:69], v[6:7]
	ds_swizzle_b32 v6, v11 offset:swizzle(SWAP,16)
	v_cvt_pk_bf16_f32 v0, v0, v1
	v_cvt_pk_bf16_f32 v1, v8, v9
	v_cvt_pk_bf16_f32 v2, v2, v3
	v_cvt_pk_bf16_f32 v3, v4, v5
	v_sub_u32_e32 v4, v10, v18
	global_store_dwordx4 v4, v[0:3], s[22:23] sc1
	s_waitcnt lgkmcnt(0)
	s_nop 0
	v_add_f32_e32 v0, v11, v6
	v_mov_b32_e32 v1, v0
	s_nop 1
	v_permlane32_swap_b32_e32 v0, v1
	s_and_saveexec_b64 s[88:89], vcc
	s_cbranch_execz .LBB0_614
	v_add_f32_e32 v0, v0, v1
	s_mov_b32 s2, 0x47800000
	v_fma_f32 v0, v0, s2, 0.5
	v_trunc_f32_e32 v0, v0
	v_mul_f32_e32 v1, 0x2f800000, v0
	v_floor_f32_e32 v1, v1
	v_fmac_f32_e32 v0, 0xcf800000, v1
	v_cvt_u32_f32_e32 v0, v0
	v_cvt_u32_f32_e32 v1, v1
	v_lshlrev_b32_e32 v2, 3, v16
	global_atomic_add_x2 v2, v[0:1], s[6:7]

.LBB0_968:
	v_mbcnt_lo_u32_b32 v64, -1, 0
	v_mbcnt_hi_u32_b32 v64, -1, v64
	s_add_i32 s95, s95, s38
	v_ashrrev_i32_e32 v65, 1, v64
	v_and_or_b32 v242, v64, 15, s95
	s_or_b32 s3, s86, s39
	v_and_b32_e32 v65, -8, v65
	v_lshlrev_b32_e32 v254, 13, v242
	v_add_lshl_u32 v241, s3, v65, 1
	v_add_u32_e32 v235, v241, v254
	global_load_dwordx4 v[244:247], v235, s[4:5]
	s_add_i32 s54, s54, s41
	v_cmp_gt_u32_e32 vcc, 16, v64
	v_add_lshl_u32 v64, v65, s39, 2
	v_add_u32_e32 v243, s54, v64
	v_add_u32_e32 v64, 0x100, v235
	global_load_dwordx4 v[248:251], v64, s[4:5]
	v_add_u32_e32 v65, 0x20000, v235
	v_add_u32_e32 v66, 0x20100, v235
	v_add_u32_e32 v67, 0x40000, v235
	v_add_u32_e32 v72, 0x40100, v235
	v_add_u32_e32 v64, 0x60000, v235
	v_add_u32_e32 v73, 0x60100, v235
	v_add_u32_e32 v74, 0x100000, v235
	v_add_u32_e32 v75, 0x100100, v235
	v_add_u32_e32 v88, 0x120000, v235
	v_add_u32_e32 v89, 0x120100, v235
	v_add_u32_e32 v90, 0x140000, v235
	v_add_u32_e32 v91, 0x140100, v235
	v_add_u32_e32 v152, 0x160000, v235
	v_add_u32_e32 v153, 0x160100, v235
	global_load_dwordx4 v[212:215], v65, s[4:5]
	global_load_dwordx4 v[208:211], v66, s[4:5]
	global_load_dwordx4 v[204:207], v67, s[4:5]
	global_load_dwordx4 v[200:203], v72, s[4:5]
	global_load_dwordx4 v[192:195], v64, s[4:5]
	global_load_dwordx4 v[164:167], v73, s[4:5]
	global_load_dwordx4 v[140:143], v74, s[4:5]
	global_load_dwordx4 v[128:131], v75, s[4:5]
	global_load_dwordx4 v[116:119], v88, s[4:5]
	global_load_dwordx4 v[108:111], v89, s[4:5]
	global_load_dwordx4 v[96:99], v90, s[4:5]
	s_nop 0
	global_load_dwordx4 v[88:91], v91, s[4:5]
	s_nop 0
	global_load_dwordx4 v[72:75], v152, s[4:5]
	global_load_dwordx4 v[64:67], v153, s[4:5]
	s_waitcnt vmcnt(0)
	ds_read_b128 v[196:199], v243
	ds_read_b128 v[188:191], v243 offset:16
	ds_read_b128 v[184:187], v243 offset:4096
	ds_read_b128 v[180:183], v243 offset:4112
	ds_read_b128 v[168:171], v243 offset:512
	ds_read_b128 v[160:163], v243 offset:528
	ds_read_b128 v[156:159], v243 offset:4608
	ds_read_b128 v[152:155], v243 offset:4624
	v_lshlrev_b32_e32 v236, 12, v242
	s_waitcnt vmcnt(0)
	v_lshlrev_b32_e32 v252, 16, v244
	v_and_b32_e32 v253, 0xffff0000, v244
	v_lshlrev_b32_e32 v244, 16, v245
	v_and_b32_e32 v245, 0xffff0000, v245
	v_lshlrev_b32_e32 v218, 16, v246
	v_and_b32_e32 v219, 0xffff0000, v246
	v_lshlrev_b32_e32 v246, 16, v247
	v_and_b32_e32 v247, 0xffff0000, v247
	s_waitcnt lgkmcnt(7)
	v_pk_fma_f32 v[178:179], v[178:179], v[198:199], v[244:245]
	s_waitcnt lgkmcnt(6)
	v_pk_fma_f32 v[244:245], v[174:175], v[190:191], v[246:247]
	v_pk_fma_f32 v[174:175], v[172:173], v[188:189], v[218:219]
	v_pk_fma_f32 v[176:177], v[176:177], v[196:197], v[252:253]
	s_nop 0
	v_cvt_pk_bf16_f32 v172, v176, v177
	v_cvt_pk_bf16_f32 v173, v178, v179
	v_cvt_pk_bf16_f32 v174, v174, v175
	v_cvt_pk_bf16_f32 v175, v244, v245
	global_store_dwordx4 v235, v[172:175], s[4:5]
	v_lshlrev_b32_e32 v176, 16, v172
	v_and_b32_e32 v177, 0xffff0000, v172
	v_lshlrev_b32_e32 v172, 16, v173
	v_and_b32_e32 v173, 0xffff0000, v173
	v_lshlrev_b32_e32 v178, 16, v174
	v_and_b32_e32 v179, 0xffff0000, v174
	v_lshlrev_b32_e32 v174, 16, v175
	v_and_b32_e32 v175, 0xffff0000, v175
	v_mul_f32_e32 v235, v177, v177
	v_mul_f32_e32 v252, v173, v173
	v_mul_f32_e32 v253, v179, v179
	v_mul_f32_e32 v220, v175, v175
	v_fmac_f32_e32 v235, v176, v176
	v_fmac_f32_e32 v252, v172, v172
	v_fmac_f32_e32 v253, v178, v178
	v_fmac_f32_e32 v220, v174, v174
	s_waitcnt lgkmcnt(5)
	v_pk_mul_f32 v[218:219], v[186:187], v[172:173]
	v_add_f32_e32 v172, v235, v252
	v_add_f32_e32 v173, v253, v220
	v_pk_mul_f32 v[244:245], v[184:185], v[176:177]
	s_waitcnt lgkmcnt(4)
	v_pk_mul_f32 v[246:247], v[182:183], v[174:175]
	v_add_f32_e32 v220, v172, v173
	v_pk_mul_f32 v[174:175], v[180:181], v[178:179]
	v_cvt_pk_bf16_f32 v172, v244, v245
	v_cvt_pk_bf16_f32 v173, v218, v219
	v_add_u32_e32 v176, v241, v236
	v_cvt_pk_bf16_f32 v174, v174, v175
	v_cvt_pk_bf16_f32 v175, v246, v247
	global_store_dwordx4 v176, v[172:175], s[18:19] sc1
	v_lshlrev_b32_e32 v176, 16, v250
	v_and_b32_e32 v177, 0xffff0000, v250
	v_lshlrev_b32_e32 v172, 16, v248
	v_and_b32_e32 v173, 0xffff0000, v248
	v_lshlrev_b32_e32 v174, 16, v249
	v_and_b32_e32 v175, 0xffff0000, v249
	v_lshlrev_b32_e32 v178, 16, v251
	v_and_b32_e32 v179, 0xffff0000, v251
	s_waitcnt lgkmcnt(3)
	v_pk_fma_f32 v[148:149], v[148:149], v[168:169], v[172:173]
	s_waitcnt lgkmcnt(2)
	v_pk_fma_f32 v[144:145], v[144:145], v[160:161], v[176:177]
	v_pk_fma_f32 v[150:151], v[150:151], v[170:171], v[174:175]
	v_pk_fma_f32 v[172:173], v[146:147], v[162:163], v[178:179]
	v_cvt_pk_bf16_f32 v146, v148, v149
	v_cvt_pk_bf16_f32 v147, v150, v151
	v_cvt_pk_bf16_f32 v148, v144, v145
	v_add_u32_e32 v144, 0x100, v241
	v_add_u32_e32 v145, v144, v254
	v_cvt_pk_bf16_f32 v149, v172, v173
	global_store_dwordx4 v145, v[146:149], s[4:5]
	v_lshlrev_b32_e32 v150, 16, v146
	v_and_b32_e32 v151, 0xffff0000, v146
	v_lshlrev_b32_e32 v146, 16, v147
	v_and_b32_e32 v147, 0xffff0000, v147
	v_mul_f32_e32 v174, v151, v151
	v_mul_f32_e32 v175, v147, v147
	v_lshlrev_b32_e32 v172, 16, v148
	v_and_b32_e32 v173, 0xffff0000, v148
	v_lshlrev_b32_e32 v148, 16, v149
	v_and_b32_e32 v149, 0xffff0000, v149
	v_fmac_f32_e32 v174, v150, v150
	v_fmac_f32_e32 v175, v146, v146
	v_add_f32_e32 v174, v174, v175
	v_mul_f32_e32 v175, v173, v173
	v_mul_f32_e32 v176, v149, v149
	v_fmac_f32_e32 v175, v172, v172
	v_fmac_f32_e32 v176, v148, v148
	v_add_f32_e32 v175, v175, v176
	v_add_f32_e32 v174, v174, v175
	v_add_f32_e32 v176, v220, v174
	s_waitcnt lgkmcnt(1)
	v_pk_mul_f32 v[174:175], v[158:159], v[146:147]
	v_pk_mul_f32 v[146:147], v[156:157], v[150:151]
	s_waitcnt lgkmcnt(0)
	v_pk_mul_f32 v[150:151], v[154:155], v[148:149]
	v_pk_mul_f32 v[148:149], v[152:153], v[172:173]
	ds_swizzle_b32 v172, v176 offset:swizzle(SWAP,16)
	v_sub_u32_e32 v145, v145, v236
	v_cvt_pk_bf16_f32 v146, v146, v147
	v_cvt_pk_bf16_f32 v147, v174, v175
	v_cvt_pk_bf16_f32 v148, v148, v149
	v_cvt_pk_bf16_f32 v149, v150, v151
	global_store_dwordx4 v145, v[146:149], s[18:19] sc1
	s_waitcnt lgkmcnt(0)
	v_add_f32_e32 v145, v176, v172
	v_mov_b32_e32 v146, v145
	s_nop 1
	v_permlane32_swap_b32_e32 v145, v146
	s_and_saveexec_b64 s[86:87], vcc
	s_cbranch_execz .LBB0_970
	v_add_f32_e32 v145, v145, v146
	s_mov_b32 s3, 0x47800000
	v_fma_f32 v145, v145, s3, 0.5
	v_trunc_f32_e32 v145, v145
	v_mul_f32_e32 v146, 0x2f800000, v145
	v_floor_f32_e32 v147, v146
	v_fmac_f32_e32 v145, 0xcf800000, v147
	v_cvt_u32_f32_e32 v146, v145
	v_cvt_u32_f32_e32 v147, v147
	v_lshlrev_b32_e32 v145, 3, v242
	global_atomic_add_x2 v145, v[146:147], s[6:7]
.LBB0_970:
	s_or_b64 exec, exec, s[86:87]
	v_or_b32_e32 v145, 16, v242
	v_lshlrev_b32_e32 v174, 13, v145
	v_lshlrev_b32_e32 v146, 16, v212
	v_and_b32_e32 v147, 0xffff0000, v212
	v_lshlrev_b32_e32 v148, 16, v213
	v_and_b32_e32 v149, 0xffff0000, v213
	v_lshlrev_b32_e32 v150, 16, v214
	v_and_b32_e32 v151, 0xffff0000, v214
	v_lshlrev_b32_e32 v172, 16, v215
	v_and_b32_e32 v173, 0xffff0000, v215
	v_pk_fma_f32 v[138:139], v[138:139], v[198:199], v[148:149]
	v_pk_fma_f32 v[136:137], v[136:137], v[196:197], v[146:147]
	v_pk_fma_f32 v[146:147], v[134:135], v[190:191], v[172:173]
	v_pk_fma_f32 v[134:135], v[132:133], v[188:189], v[150:151]
	v_cvt_pk_bf16_f32 v132, v136, v137
	v_cvt_pk_bf16_f32 v133, v138, v139
	v_add_u32_e32 v148, v241, v174
	v_cvt_pk_bf16_f32 v134, v134, v135
	v_cvt_pk_bf16_f32 v135, v146, v147
	global_store_dwordx4 v148, v[132:135], s[4:5]
	v_lshlrev_b32_e32 v136, 16, v132
	v_and_b32_e32 v137, 0xffff0000, v132
	v_lshlrev_b32_e32 v132, 16, v133
	v_and_b32_e32 v133, 0xffff0000, v133
	v_mul_f32_e32 v146, v137, v137
	v_mul_f32_e32 v147, v133, v133
	v_lshlrev_b32_e32 v138, 16, v134
	v_and_b32_e32 v139, 0xffff0000, v134
	v_lshlrev_b32_e32 v134, 16, v135
	v_and_b32_e32 v135, 0xffff0000, v135
	v_fmac_f32_e32 v146, v136, v136
	v_fmac_f32_e32 v147, v132, v132
	v_add_f32_e32 v146, v146, v147
	v_mul_f32_e32 v147, v139, v139
	v_mul_f32_e32 v149, v135, v135
	v_fmac_f32_e32 v147, v138, v138
	v_fmac_f32_e32 v149, v134, v134
	v_add_f32_e32 v147, v147, v149
	v_add_f32_e32 v149, v146, v147
	v_pk_mul_f32 v[146:147], v[186:187], v[132:133]
	v_pk_mul_f32 v[132:133], v[184:185], v[136:137]
	v_pk_mul_f32 v[136:137], v[182:183], v[134:135]
	v_pk_mul_f32 v[134:135], v[180:181], v[138:139]
	v_cvt_pk_bf16_f32 v132, v132, v133
	v_cvt_pk_bf16_f32 v133, v146, v147
	v_lshlrev_b32_e32 v146, 12, v145
	v_cvt_pk_bf16_f32 v134, v134, v135
	v_cvt_pk_bf16_f32 v135, v136, v137
	v_sub_u32_e32 v136, v148, v146
	global_store_dwordx4 v136, v[132:135], s[18:19] sc1
	v_lshlrev_b32_e32 v136, 16, v210
	v_and_b32_e32 v137, 0xffff0000, v210
	v_lshlrev_b32_e32 v132, 16, v208
	v_and_b32_e32 v133, 0xffff0000, v208
	v_lshlrev_b32_e32 v134, 16, v209
	v_and_b32_e32 v135, 0xffff0000, v209
	v_lshlrev_b32_e32 v138, 16, v211
	v_and_b32_e32 v139, 0xffff0000, v211
	v_pk_fma_f32 v[126:127], v[126:127], v[170:171], v[134:135]
	v_pk_fma_f32 v[124:125], v[124:125], v[168:169], v[132:133]
	v_pk_fma_f32 v[132:133], v[122:123], v[162:163], v[138:139]
	v_pk_fma_f32 v[122:123], v[120:121], v[160:161], v[136:137]
	v_cvt_pk_bf16_f32 v120, v124, v125
	v_cvt_pk_bf16_f32 v121, v126, v127
	v_add_u32_e32 v134, v144, v174
	v_cvt_pk_bf16_f32 v122, v122, v123
	v_cvt_pk_bf16_f32 v123, v132, v133
	global_store_dwordx4 v134, v[120:123], s[4:5]
	v_lshlrev_b32_e32 v124, 16, v120
	v_and_b32_e32 v125, 0xffff0000, v120
	v_lshlrev_b32_e32 v120, 16, v121
	v_and_b32_e32 v121, 0xffff0000, v121
	v_mul_f32_e32 v132, v125, v125
	v_mul_f32_e32 v133, v121, v121
	v_lshlrev_b32_e32 v126, 16, v122
	v_and_b32_e32 v127, 0xffff0000, v122
	v_lshlrev_b32_e32 v122, 16, v123
	v_and_b32_e32 v123, 0xffff0000, v123
	v_fmac_f32_e32 v132, v124, v124
	v_fmac_f32_e32 v133, v120, v120
	v_add_f32_e32 v132, v132, v133
	v_mul_f32_e32 v133, v127, v127
	v_mul_f32_e32 v135, v123, v123
	v_fmac_f32_e32 v133, v126, v126
	v_fmac_f32_e32 v135, v122, v122
	v_add_f32_e32 v133, v133, v135
	v_add_f32_e32 v132, v132, v133
	v_add_f32_e32 v135, v149, v132
	v_pk_mul_f32 v[132:133], v[158:159], v[120:121]
	v_pk_mul_f32 v[120:121], v[156:157], v[124:125]
	v_pk_mul_f32 v[124:125], v[154:155], v[122:123]
	v_pk_mul_f32 v[122:123], v[152:153], v[126:127]
	ds_swizzle_b32 v126, v135 offset:swizzle(SWAP,16)
	v_cvt_pk_bf16_f32 v120, v120, v121
	v_cvt_pk_bf16_f32 v121, v132, v133
	v_cvt_pk_bf16_f32 v122, v122, v123
	v_cvt_pk_bf16_f32 v123, v124, v125
	v_sub_u32_e32 v124, v134, v146
	global_store_dwordx4 v124, v[120:123], s[18:19] sc1
	s_waitcnt lgkmcnt(0)
	s_nop 0
	v_add_f32_e32 v120, v135, v126
	v_mov_b32_e32 v121, v120
	s_nop 1
	v_permlane32_swap_b32_e32 v120, v121
	s_and_saveexec_b64 s[86:87], vcc
	s_cbranch_execz .LBB0_972
	v_add_f32_e32 v120, v120, v121
	s_mov_b32 s3, 0x47800000
	v_fma_f32 v120, v120, s3, 0.5
	v_trunc_f32_e32 v120, v120
	v_mul_f32_e32 v121, 0x2f800000, v120
	v_floor_f32_e32 v121, v121
	v_fmac_f32_e32 v120, 0xcf800000, v121
	v_cvt_u32_f32_e32 v120, v120
	v_cvt_u32_f32_e32 v121, v121
	v_lshlrev_b32_e32 v122, 3, v145
	global_atomic_add_x2 v122, v[120:121], s[6:7]
.LBB0_972:
	s_or_b64 exec, exec, s[86:87]
	v_or_b32_e32 v120, 32, v242
	v_lshlrev_b32_e32 v121, 13, v120
	v_lshlrev_b32_e32 v122, 16, v204
	v_and_b32_e32 v123, 0xffff0000, v204
	v_lshlrev_b32_e32 v124, 16, v205
	v_and_b32_e32 v125, 0xffff0000, v205
	v_lshlrev_b32_e32 v126, 16, v206
	v_and_b32_e32 v127, 0xffff0000, v206
	v_lshlrev_b32_e32 v132, 16, v207
	v_and_b32_e32 v133, 0xffff0000, v207
	v_pk_fma_f32 v[114:115], v[114:115], v[198:199], v[124:125]
	v_pk_fma_f32 v[112:113], v[112:113], v[196:197], v[122:123]
	v_pk_fma_f32 v[122:123], v[106:107], v[190:191], v[132:133]
	v_pk_fma_f32 v[106:107], v[104:105], v[188:189], v[126:127]
	v_cvt_pk_bf16_f32 v104, v112, v113
	v_cvt_pk_bf16_f32 v105, v114, v115
	v_add_u32_e32 v124, v241, v121
	v_cvt_pk_bf16_f32 v106, v106, v107
	v_cvt_pk_bf16_f32 v107, v122, v123
	global_store_dwordx4 v124, v[104:107], s[4:5]
	v_lshlrev_b32_e32 v112, 16, v104
	v_and_b32_e32 v113, 0xffff0000, v104
	v_lshlrev_b32_e32 v104, 16, v105
	v_and_b32_e32 v105, 0xffff0000, v105
	v_mul_f32_e32 v122, v113, v113
	v_mul_f32_e32 v123, v105, v105
	v_lshlrev_b32_e32 v114, 16, v106
	v_and_b32_e32 v115, 0xffff0000, v106
	v_lshlrev_b32_e32 v106, 16, v107
	v_and_b32_e32 v107, 0xffff0000, v107
	v_fmac_f32_e32 v122, v112, v112
	v_fmac_f32_e32 v123, v104, v104
	v_add_f32_e32 v122, v122, v123
	v_mul_f32_e32 v123, v115, v115
	v_mul_f32_e32 v125, v107, v107
	v_fmac_f32_e32 v123, v114, v114
	v_fmac_f32_e32 v125, v106, v106
	v_add_f32_e32 v123, v123, v125
	v_add_f32_e32 v125, v122, v123
	v_pk_mul_f32 v[122:123], v[186:187], v[104:105]
	v_pk_mul_f32 v[104:105], v[184:185], v[112:113]
	v_pk_mul_f32 v[112:113], v[182:183], v[106:107]
	v_pk_mul_f32 v[106:107], v[180:181], v[114:115]
	v_cvt_pk_bf16_f32 v104, v104, v105
	v_cvt_pk_bf16_f32 v105, v122, v123
	v_lshlrev_b32_e32 v122, 12, v120
	v_cvt_pk_bf16_f32 v106, v106, v107
	v_cvt_pk_bf16_f32 v107, v112, v113
	v_sub_u32_e32 v112, v124, v122
	global_store_dwordx4 v112, v[104:107], s[18:19] sc1
	v_lshlrev_b32_e32 v112, 16, v202
	v_and_b32_e32 v113, 0xffff0000, v202
	v_lshlrev_b32_e32 v104, 16, v200
	v_and_b32_e32 v105, 0xffff0000, v200
	v_lshlrev_b32_e32 v106, 16, v201
	v_and_b32_e32 v107, 0xffff0000, v201
	v_lshlrev_b32_e32 v114, 16, v203
	v_and_b32_e32 v115, 0xffff0000, v203
	v_pk_fma_f32 v[102:103], v[102:103], v[170:171], v[106:107]
	v_pk_fma_f32 v[100:101], v[100:101], v[168:169], v[104:105]
	v_pk_fma_f32 v[104:105], v[94:95], v[162:163], v[114:115]
	v_pk_fma_f32 v[94:95], v[92:93], v[160:161], v[112:113]
	v_cvt_pk_bf16_f32 v92, v100, v101
	v_cvt_pk_bf16_f32 v93, v102, v103
	v_add_u32_e32 v106, v144, v121
	v_cvt_pk_bf16_f32 v94, v94, v95
	v_cvt_pk_bf16_f32 v95, v104, v105
	global_store_dwordx4 v106, v[92:95], s[4:5]
	v_lshlrev_b32_e32 v100, 16, v92
	v_and_b32_e32 v101, 0xffff0000, v92
	v_lshlrev_b32_e32 v92, 16, v93
	v_and_b32_e32 v93, 0xffff0000, v93
	v_mul_f32_e32 v104, v101, v101
	v_mul_f32_e32 v105, v93, v93
	v_lshlrev_b32_e32 v102, 16, v94
	v_and_b32_e32 v103, 0xffff0000, v94
	v_lshlrev_b32_e32 v94, 16, v95
	v_and_b32_e32 v95, 0xffff0000, v95
	v_fmac_f32_e32 v104, v100, v100
	v_fmac_f32_e32 v105, v92, v92
	v_add_f32_e32 v104, v104, v105
	v_mul_f32_e32 v105, v103, v103
	v_mul_f32_e32 v107, v95, v95
	v_fmac_f32_e32 v105, v102, v102
	v_fmac_f32_e32 v107, v94, v94
	v_add_f32_e32 v105, v105, v107
	v_add_f32_e32 v104, v104, v105
	v_add_f32_e32 v107, v125, v104
	v_pk_mul_f32 v[104:105], v[158:159], v[92:93]
	v_pk_mul_f32 v[92:93], v[156:157], v[100:101]
	v_pk_mul_f32 v[100:101], v[154:155], v[94:95]
	v_pk_mul_f32 v[94:95], v[152:153], v[102:103]
	ds_swizzle_b32 v102, v107 offset:swizzle(SWAP,16)
	v_cvt_pk_bf16_f32 v92, v92, v93
	v_cvt_pk_bf16_f32 v93, v104, v105
	v_cvt_pk_bf16_f32 v94, v94, v95
	v_cvt_pk_bf16_f32 v95, v100, v101
	v_sub_u32_e32 v100, v106, v122
	global_store_dwordx4 v100, v[92:95], s[18:19] sc1
	s_waitcnt lgkmcnt(0)
	s_nop 0
	v_add_f32_e32 v92, v107, v102
	v_mov_b32_e32 v93, v92
	s_nop 1
	v_permlane32_swap_b32_e32 v92, v93
	s_and_saveexec_b64 s[86:87], vcc
	s_cbranch_execz .LBB0_974
	v_add_f32_e32 v92, v92, v93
	s_mov_b32 s3, 0x47800000
	v_fma_f32 v92, v92, s3, 0.5
	v_trunc_f32_e32 v92, v92
	v_mul_f32_e32 v93, 0x2f800000, v92
	v_floor_f32_e32 v93, v93
	v_fmac_f32_e32 v92, 0xcf800000, v93
	v_cvt_u32_f32_e32 v92, v92
	v_cvt_u32_f32_e32 v93, v93
	v_lshlrev_b32_e32 v94, 3, v120
	global_atomic_add_x2 v94, v[92:93], s[6:7]
.LBB0_974:
	s_or_b64 exec, exec, s[86:87]
	v_or_b32_e32 v92, 48, v242
	v_lshlrev_b32_e32 v93, 13, v92
	v_lshlrev_b32_e32 v94, 16, v192
	v_and_b32_e32 v95, 0xffff0000, v192
	v_lshlrev_b32_e32 v100, 16, v193
	v_and_b32_e32 v101, 0xffff0000, v193
	v_lshlrev_b32_e32 v102, 16, v194
	v_and_b32_e32 v103, 0xffff0000, v194
	v_lshlrev_b32_e32 v104, 16, v195
	v_and_b32_e32 v105, 0xffff0000, v195
	v_pk_fma_f32 v[86:87], v[86:87], v[198:199], v[100:101]
	v_pk_fma_f32 v[84:85], v[84:85], v[196:197], v[94:95]
	v_pk_fma_f32 v[94:95], v[82:83], v[190:191], v[104:105]
	v_pk_fma_f32 v[82:83], v[80:81], v[188:189], v[102:103]
	v_cvt_pk_bf16_f32 v80, v84, v85
	v_cvt_pk_bf16_f32 v81, v86, v87
	v_add_u32_e32 v100, v241, v93
	v_cvt_pk_bf16_f32 v82, v82, v83
	v_cvt_pk_bf16_f32 v83, v94, v95
	global_store_dwordx4 v100, v[80:83], s[4:5]
	v_lshlrev_b32_e32 v84, 16, v80
	v_and_b32_e32 v85, 0xffff0000, v80
	v_lshlrev_b32_e32 v80, 16, v81
	v_and_b32_e32 v81, 0xffff0000, v81
	v_mul_f32_e32 v94, v85, v85
	v_mul_f32_e32 v95, v81, v81
	v_lshlrev_b32_e32 v86, 16, v82
	v_and_b32_e32 v87, 0xffff0000, v82
	v_lshlrev_b32_e32 v82, 16, v83
	v_and_b32_e32 v83, 0xffff0000, v83
	v_fmac_f32_e32 v94, v84, v84
	v_fmac_f32_e32 v95, v80, v80
	v_add_f32_e32 v94, v94, v95
	v_mul_f32_e32 v95, v87, v87
	v_mul_f32_e32 v101, v83, v83
	v_fmac_f32_e32 v95, v86, v86
	v_fmac_f32_e32 v101, v82, v82
	v_add_f32_e32 v95, v95, v101
	v_add_f32_e32 v101, v94, v95
	v_pk_mul_f32 v[94:95], v[186:187], v[80:81]
	v_pk_mul_f32 v[80:81], v[184:185], v[84:85]
	v_pk_mul_f32 v[84:85], v[182:183], v[82:83]
	v_pk_mul_f32 v[82:83], v[180:181], v[86:87]
	v_cvt_pk_bf16_f32 v80, v80, v81
	v_cvt_pk_bf16_f32 v81, v94, v95
	v_lshlrev_b32_e32 v94, 12, v92
	v_cvt_pk_bf16_f32 v82, v82, v83
	v_cvt_pk_bf16_f32 v83, v84, v85
	v_sub_u32_e32 v84, v100, v94
	global_store_dwordx4 v84, v[80:83], s[18:19] sc1
	v_lshlrev_b32_e32 v84, 16, v166
	v_and_b32_e32 v85, 0xffff0000, v166
	v_lshlrev_b32_e32 v80, 16, v164
	v_and_b32_e32 v81, 0xffff0000, v164
	v_lshlrev_b32_e32 v82, 16, v165
	v_and_b32_e32 v83, 0xffff0000, v165
	v_lshlrev_b32_e32 v86, 16, v167
	v_and_b32_e32 v87, 0xffff0000, v167
	v_pk_fma_f32 v[78:79], v[78:79], v[170:171], v[82:83]
	v_pk_fma_f32 v[76:77], v[76:77], v[168:169], v[80:81]
	v_pk_fma_f32 v[80:81], v[70:71], v[162:163], v[86:87]
	v_pk_fma_f32 v[70:71], v[68:69], v[160:161], v[84:85]
	v_cvt_pk_bf16_f32 v68, v76, v77
	v_cvt_pk_bf16_f32 v69, v78, v79
	v_add_u32_e32 v82, v144, v93
	v_cvt_pk_bf16_f32 v70, v70, v71
	v_cvt_pk_bf16_f32 v71, v80, v81
	global_store_dwordx4 v82, v[68:71], s[4:5]
	v_lshlrev_b32_e32 v76, 16, v68
	v_and_b32_e32 v77, 0xffff0000, v68
	v_lshlrev_b32_e32 v68, 16, v69
	v_and_b32_e32 v69, 0xffff0000, v69
	v_mul_f32_e32 v80, v77, v77
	v_mul_f32_e32 v81, v69, v69
	v_lshlrev_b32_e32 v78, 16, v70
	v_and_b32_e32 v79, 0xffff0000, v70
	v_lshlrev_b32_e32 v70, 16, v71
	v_and_b32_e32 v71, 0xffff0000, v71
	v_fmac_f32_e32 v80, v76, v76
	v_fmac_f32_e32 v81, v68, v68
	v_add_f32_e32 v80, v80, v81
	v_mul_f32_e32 v81, v79, v79
	v_mul_f32_e32 v83, v71, v71
	v_fmac_f32_e32 v81, v78, v78
	v_fmac_f32_e32 v83, v70, v70
	v_add_f32_e32 v81, v81, v83
	v_add_f32_e32 v80, v80, v81
	v_add_f32_e32 v83, v101, v80
	v_pk_mul_f32 v[80:81], v[158:159], v[68:69]
	v_pk_mul_f32 v[68:69], v[156:157], v[76:77]
	v_pk_mul_f32 v[76:77], v[154:155], v[70:71]
	v_pk_mul_f32 v[70:71], v[152:153], v[78:79]
	ds_swizzle_b32 v78, v83 offset:swizzle(SWAP,16)
	v_cvt_pk_bf16_f32 v68, v68, v69
	v_cvt_pk_bf16_f32 v69, v80, v81
	v_cvt_pk_bf16_f32 v70, v70, v71
	v_cvt_pk_bf16_f32 v71, v76, v77
	v_sub_u32_e32 v76, v82, v94
	global_store_dwordx4 v76, v[68:71], s[18:19] sc1
	s_waitcnt lgkmcnt(0)
	s_nop 0
	v_add_f32_e32 v68, v83, v78
	v_mov_b32_e32 v69, v68
	s_nop 1
	v_permlane32_swap_b32_e32 v68, v69
	s_and_saveexec_b64 s[86:87], vcc
	s_cbranch_execz .LBB0_976
	v_add_f32_e32 v68, v68, v69
	s_mov_b32 s3, 0x47800000
	v_fma_f32 v68, v68, s3, 0.5
	v_trunc_f32_e32 v68, v68
	v_mul_f32_e32 v69, 0x2f800000, v68
	v_floor_f32_e32 v69, v69
	v_fmac_f32_e32 v68, 0xcf800000, v69
	v_cvt_u32_f32_e32 v68, v68
	v_cvt_u32_f32_e32 v69, v69
	v_lshlrev_b32_e32 v70, 3, v92
	global_atomic_add_x2 v70, v[68:69], s[6:7]
.LBB0_976:
	s_or_b64 exec, exec, s[86:87]
	v_add_u32_e32 v120, 0x80, v242
	v_lshlrev_b32_e32 v121, 13, v120
	v_lshlrev_b32_e32 v122, 16, v140
	v_and_b32_e32 v123, 0xffff0000, v140
	v_lshlrev_b32_e32 v124, 16, v141
	v_and_b32_e32 v125, 0xffff0000, v141
	v_lshlrev_b32_e32 v126, 16, v142
	v_and_b32_e32 v127, 0xffff0000, v142
	v_lshlrev_b32_e32 v132, 16, v143
	v_and_b32_e32 v133, 0xffff0000, v143
	ds_read_b128 v[112:115], v243 offset:2048
	ds_read_b128 v[104:107], v243 offset:2064
	ds_read_b128 v[100:103], v243 offset:6144
	ds_read_b128 v[92:95], v243 offset:6160
	ds_read_b128 v[84:87], v243 offset:2560
	ds_read_b128 v[80:83], v243 offset:2576
	ds_read_b128 v[76:79], v243 offset:6656
	ds_read_b128 v[68:71], v243 offset:6672
	s_waitcnt lgkmcnt(7)
	v_pk_fma_f32 v[62:63], v[62:63], v[114:115], v[124:125]
	v_pk_fma_f32 v[60:61], v[60:61], v[112:113], v[122:123]
	s_waitcnt lgkmcnt(6)
	v_pk_fma_f32 v[122:123], v[58:59], v[106:107], v[132:133]
	v_pk_fma_f32 v[58:59], v[56:57], v[104:105], v[126:127]
	v_cvt_pk_bf16_f32 v56, v60, v61
	v_cvt_pk_bf16_f32 v57, v62, v63
	v_add_u32_e32 v124, v241, v121
	v_cvt_pk_bf16_f32 v58, v58, v59
	v_cvt_pk_bf16_f32 v59, v122, v123
	global_store_dwordx4 v124, v[56:59], s[4:5]
	v_lshlrev_b32_e32 v60, 16, v56
	v_and_b32_e32 v61, 0xffff0000, v56
	v_lshlrev_b32_e32 v56, 16, v57
	v_and_b32_e32 v57, 0xffff0000, v57
	v_mul_f32_e32 v122, v61, v61
	v_mul_f32_e32 v123, v57, v57
	v_lshlrev_b32_e32 v62, 16, v58
	v_and_b32_e32 v63, 0xffff0000, v58
	v_lshlrev_b32_e32 v58, 16, v59
	v_and_b32_e32 v59, 0xffff0000, v59
	v_fmac_f32_e32 v122, v60, v60
	v_fmac_f32_e32 v123, v56, v56
	v_add_f32_e32 v122, v122, v123
	v_mul_f32_e32 v123, v63, v63
	v_mul_f32_e32 v125, v59, v59
	v_fmac_f32_e32 v123, v62, v62
	v_fmac_f32_e32 v125, v58, v58
	v_add_f32_e32 v123, v123, v125
	v_add_f32_e32 v125, v122, v123
	s_waitcnt lgkmcnt(5)
	v_pk_mul_f32 v[122:123], v[102:103], v[56:57]
	v_pk_mul_f32 v[56:57], v[100:101], v[60:61]
	s_waitcnt lgkmcnt(4)
	v_pk_mul_f32 v[60:61], v[94:95], v[58:59]
	v_pk_mul_f32 v[58:59], v[92:93], v[62:63]
	v_cvt_pk_bf16_f32 v56, v56, v57
	v_cvt_pk_bf16_f32 v57, v122, v123
	v_lshlrev_b32_e32 v122, 12, v120
	v_cvt_pk_bf16_f32 v58, v58, v59
	v_cvt_pk_bf16_f32 v59, v60, v61
	v_sub_u32_e32 v60, v124, v122
	global_store_dwordx4 v60, v[56:59], s[18:19] sc1
	v_lshlrev_b32_e32 v60, 16, v130
	v_and_b32_e32 v61, 0xffff0000, v130
	v_lshlrev_b32_e32 v56, 16, v128
	v_and_b32_e32 v57, 0xffff0000, v128
	v_lshlrev_b32_e32 v58, 16, v129
	v_and_b32_e32 v59, 0xffff0000, v129
	v_lshlrev_b32_e32 v62, 16, v131
	v_and_b32_e32 v63, 0xffff0000, v131
	s_waitcnt lgkmcnt(3)
	v_pk_fma_f32 v[54:55], v[54:55], v[86:87], v[58:59]
	v_pk_fma_f32 v[52:53], v[52:53], v[84:85], v[56:57]
	s_waitcnt lgkmcnt(2)
	v_pk_fma_f32 v[56:57], v[50:51], v[82:83], v[62:63]
	v_pk_fma_f32 v[50:51], v[48:49], v[80:81], v[60:61]
	v_cvt_pk_bf16_f32 v48, v52, v53
	v_cvt_pk_bf16_f32 v49, v54, v55
	v_add_u32_e32 v58, v144, v121
	v_cvt_pk_bf16_f32 v50, v50, v51
	v_cvt_pk_bf16_f32 v51, v56, v57
	global_store_dwordx4 v58, v[48:51], s[4:5]
	v_lshlrev_b32_e32 v52, 16, v48
	v_and_b32_e32 v53, 0xffff0000, v48
	v_lshlrev_b32_e32 v48, 16, v49
	v_and_b32_e32 v49, 0xffff0000, v49
	v_mul_f32_e32 v56, v53, v53
	v_mul_f32_e32 v57, v49, v49
	v_lshlrev_b32_e32 v54, 16, v50
	v_and_b32_e32 v55, 0xffff0000, v50
	v_lshlrev_b32_e32 v50, 16, v51
	v_and_b32_e32 v51, 0xffff0000, v51
	v_fmac_f32_e32 v56, v52, v52
	v_fmac_f32_e32 v57, v48, v48
	v_add_f32_e32 v56, v56, v57
	v_mul_f32_e32 v57, v55, v55
	v_mul_f32_e32 v59, v51, v51
	v_fmac_f32_e32 v57, v54, v54
	v_fmac_f32_e32 v59, v50, v50
	v_add_f32_e32 v57, v57, v59
	v_add_f32_e32 v56, v56, v57
	v_add_f32_e32 v59, v125, v56
	s_waitcnt lgkmcnt(1)
	v_pk_mul_f32 v[56:57], v[78:79], v[48:49]
	v_pk_mul_f32 v[48:49], v[76:77], v[52:53]
	s_waitcnt lgkmcnt(0)
	v_pk_mul_f32 v[52:53], v[70:71], v[50:51]
	v_pk_mul_f32 v[50:51], v[68:69], v[54:55]
	ds_swizzle_b32 v54, v59 offset:swizzle(SWAP,16)
	v_cvt_pk_bf16_f32 v48, v48, v49
	v_cvt_pk_bf16_f32 v49, v56, v57
	v_cvt_pk_bf16_f32 v50, v50, v51
	v_cvt_pk_bf16_f32 v51, v52, v53
	v_sub_u32_e32 v52, v58, v122
	global_store_dwordx4 v52, v[48:51], s[18:19] sc1
	s_waitcnt lgkmcnt(0)
	s_nop 0
	v_add_f32_e32 v48, v59, v54
	v_mov_b32_e32 v49, v48
	s_nop 1
	v_permlane32_swap_b32_e32 v48, v49
	s_and_saveexec_b64 s[86:87], vcc
	s_cbranch_execz .LBB0_978
	v_add_f32_e32 v48, v48, v49
	s_mov_b32 s3, 0x47800000
	v_fma_f32 v48, v48, s3, 0.5
	v_trunc_f32_e32 v48, v48
	v_mul_f32_e32 v49, 0x2f800000, v48
	v_floor_f32_e32 v49, v49
	v_fmac_f32_e32 v48, 0xcf800000, v49
	v_cvt_u32_f32_e32 v48, v48
	v_cvt_u32_f32_e32 v49, v49
	v_lshlrev_b32_e32 v50, 3, v120
	global_atomic_add_x2 v50, v[48:49], s[6:7]
.LBB0_978:
	s_or_b64 exec, exec, s[86:87]
	v_add_u32_e32 v48, 0x90, v242
	v_lshlrev_b32_e32 v49, 13, v48
	v_lshlrev_b32_e32 v50, 16, v116
	v_and_b32_e32 v51, 0xffff0000, v116
	v_lshlrev_b32_e32 v52, 16, v117
	v_and_b32_e32 v53, 0xffff0000, v117
	v_lshlrev_b32_e32 v54, 16, v118
	v_and_b32_e32 v55, 0xffff0000, v118
	v_lshlrev_b32_e32 v56, 16, v119
	v_and_b32_e32 v57, 0xffff0000, v119
	v_pk_fma_f32 v[46:47], v[46:47], v[114:115], v[52:53]
	v_pk_fma_f32 v[44:45], v[44:45], v[112:113], v[50:51]
	v_pk_fma_f32 v[50:51], v[42:43], v[106:107], v[56:57]
	v_pk_fma_f32 v[42:43], v[40:41], v[104:105], v[54:55]
	v_cvt_pk_bf16_f32 v40, v44, v45
	v_cvt_pk_bf16_f32 v41, v46, v47
	v_add_u32_e32 v52, v241, v49
	v_cvt_pk_bf16_f32 v42, v42, v43
	v_cvt_pk_bf16_f32 v43, v50, v51
	global_store_dwordx4 v52, v[40:43], s[4:5]
	v_lshlrev_b32_e32 v44, 16, v40
	v_and_b32_e32 v45, 0xffff0000, v40
	v_lshlrev_b32_e32 v40, 16, v41
	v_and_b32_e32 v41, 0xffff0000, v41
	v_mul_f32_e32 v50, v45, v45
	v_mul_f32_e32 v51, v41, v41
	v_lshlrev_b32_e32 v46, 16, v42
	v_and_b32_e32 v47, 0xffff0000, v42
	v_lshlrev_b32_e32 v42, 16, v43
	v_and_b32_e32 v43, 0xffff0000, v43
	v_fmac_f32_e32 v50, v44, v44
	v_fmac_f32_e32 v51, v40, v40
	v_add_f32_e32 v50, v50, v51
	v_mul_f32_e32 v51, v47, v47
	v_mul_f32_e32 v53, v43, v43
	v_fmac_f32_e32 v51, v46, v46
	v_fmac_f32_e32 v53, v42, v42
	v_add_f32_e32 v51, v51, v53
	v_add_f32_e32 v53, v50, v51
	v_pk_mul_f32 v[50:51], v[102:103], v[40:41]
	v_pk_mul_f32 v[40:41], v[100:101], v[44:45]
	v_pk_mul_f32 v[44:45], v[94:95], v[42:43]
	v_pk_mul_f32 v[42:43], v[92:93], v[46:47]
	v_cvt_pk_bf16_f32 v40, v40, v41
	v_cvt_pk_bf16_f32 v41, v50, v51
	v_lshlrev_b32_e32 v50, 12, v48
	v_cvt_pk_bf16_f32 v42, v42, v43
	v_cvt_pk_bf16_f32 v43, v44, v45
	v_sub_u32_e32 v44, v52, v50
	global_store_dwordx4 v44, v[40:43], s[18:19] sc1
	v_lshlrev_b32_e32 v44, 16, v110
	v_and_b32_e32 v45, 0xffff0000, v110
	v_lshlrev_b32_e32 v40, 16, v108
	v_and_b32_e32 v41, 0xffff0000, v108
	v_lshlrev_b32_e32 v42, 16, v109
	v_and_b32_e32 v43, 0xffff0000, v109
	v_lshlrev_b32_e32 v46, 16, v111
	v_and_b32_e32 v47, 0xffff0000, v111
	v_pk_fma_f32 v[38:39], v[38:39], v[86:87], v[42:43]
	v_pk_fma_f32 v[36:37], v[36:37], v[84:85], v[40:41]
	v_pk_fma_f32 v[40:41], v[34:35], v[82:83], v[46:47]
	v_pk_fma_f32 v[34:35], v[32:33], v[80:81], v[44:45]
	v_cvt_pk_bf16_f32 v32, v36, v37
	v_cvt_pk_bf16_f32 v33, v38, v39
	v_add_u32_e32 v42, v144, v49
	v_cvt_pk_bf16_f32 v34, v34, v35
	v_cvt_pk_bf16_f32 v35, v40, v41
	global_store_dwordx4 v42, v[32:35], s[4:5]
	v_lshlrev_b32_e32 v36, 16, v32
	v_and_b32_e32 v37, 0xffff0000, v32
	v_lshlrev_b32_e32 v32, 16, v33
	v_and_b32_e32 v33, 0xffff0000, v33
	v_mul_f32_e32 v40, v37, v37
	v_mul_f32_e32 v41, v33, v33
	v_lshlrev_b32_e32 v38, 16, v34
	v_and_b32_e32 v39, 0xffff0000, v34
	v_lshlrev_b32_e32 v34, 16, v35
	v_and_b32_e32 v35, 0xffff0000, v35
	v_fmac_f32_e32 v40, v36, v36
	v_fmac_f32_e32 v41, v32, v32
	v_add_f32_e32 v40, v40, v41
	v_mul_f32_e32 v41, v39, v39
	v_mul_f32_e32 v43, v35, v35
	v_fmac_f32_e32 v41, v38, v38
	v_fmac_f32_e32 v43, v34, v34
	v_add_f32_e32 v41, v41, v43
	v_add_f32_e32 v40, v40, v41
	v_add_f32_e32 v43, v53, v40
	v_pk_mul_f32 v[40:41], v[78:79], v[32:33]
	v_pk_mul_f32 v[32:33], v[76:77], v[36:37]
	v_pk_mul_f32 v[36:37], v[70:71], v[34:35]
	v_pk_mul_f32 v[34:35], v[68:69], v[38:39]
	ds_swizzle_b32 v38, v43 offset:swizzle(SWAP,16)
	v_cvt_pk_bf16_f32 v32, v32, v33
	v_cvt_pk_bf16_f32 v33, v40, v41
	v_cvt_pk_bf16_f32 v34, v34, v35
	v_cvt_pk_bf16_f32 v35, v36, v37
	v_sub_u32_e32 v36, v42, v50
	global_store_dwordx4 v36, v[32:35], s[18:19] sc1
	s_waitcnt lgkmcnt(0)
	s_nop 0
	v_add_f32_e32 v32, v43, v38
	v_mov_b32_e32 v33, v32
	s_nop 1
	v_permlane32_swap_b32_e32 v32, v33
	s_and_saveexec_b64 s[86:87], vcc
	s_cbranch_execz .LBB0_980
	v_add_f32_e32 v32, v32, v33
	s_mov_b32 s3, 0x47800000
	v_fma_f32 v32, v32, s3, 0.5
	v_trunc_f32_e32 v32, v32
	v_mul_f32_e32 v33, 0x2f800000, v32
	v_floor_f32_e32 v33, v33
	v_fmac_f32_e32 v32, 0xcf800000, v33
	v_cvt_u32_f32_e32 v32, v32
	v_cvt_u32_f32_e32 v33, v33
	v_lshlrev_b32_e32 v34, 3, v48
	global_atomic_add_x2 v34, v[32:33], s[6:7]
.LBB0_980:
	s_or_b64 exec, exec, s[86:87]
	v_add_u32_e32 v32, 0xa0, v242
	v_lshlrev_b32_e32 v33, 13, v32
	v_lshlrev_b32_e32 v34, 16, v96
	v_and_b32_e32 v35, 0xffff0000, v96
	v_lshlrev_b32_e32 v36, 16, v97
	v_and_b32_e32 v37, 0xffff0000, v97
	v_lshlrev_b32_e32 v38, 16, v98
	v_and_b32_e32 v39, 0xffff0000, v98
	v_lshlrev_b32_e32 v40, 16, v99
	v_and_b32_e32 v41, 0xffff0000, v99
	v_pk_fma_f32 v[30:31], v[30:31], v[114:115], v[36:37]
	v_pk_fma_f32 v[28:29], v[28:29], v[112:113], v[34:35]
	v_pk_fma_f32 v[34:35], v[26:27], v[106:107], v[40:41]
	v_pk_fma_f32 v[26:27], v[24:25], v[104:105], v[38:39]
	v_cvt_pk_bf16_f32 v24, v28, v29
	v_cvt_pk_bf16_f32 v25, v30, v31
	v_add_u32_e32 v36, v241, v33
	v_cvt_pk_bf16_f32 v26, v26, v27
	v_cvt_pk_bf16_f32 v27, v34, v35
	global_store_dwordx4 v36, v[24:27], s[4:5]
	v_lshlrev_b32_e32 v28, 16, v24
	v_and_b32_e32 v29, 0xffff0000, v24
	v_lshlrev_b32_e32 v24, 16, v25
	v_and_b32_e32 v25, 0xffff0000, v25
	v_mul_f32_e32 v34, v29, v29
	v_mul_f32_e32 v35, v25, v25
	v_lshlrev_b32_e32 v30, 16, v26
	v_and_b32_e32 v31, 0xffff0000, v26
	v_lshlrev_b32_e32 v26, 16, v27
	v_and_b32_e32 v27, 0xffff0000, v27
	v_fmac_f32_e32 v34, v28, v28
	v_fmac_f32_e32 v35, v24, v24
	v_add_f32_e32 v34, v34, v35
	v_mul_f32_e32 v35, v31, v31
	v_mul_f32_e32 v37, v27, v27
	v_fmac_f32_e32 v35, v30, v30
	v_fmac_f32_e32 v37, v26, v26
	v_add_f32_e32 v35, v35, v37
	v_add_f32_e32 v37, v34, v35
	v_pk_mul_f32 v[34:35], v[102:103], v[24:25]
	v_pk_mul_f32 v[24:25], v[100:101], v[28:29]
	v_pk_mul_f32 v[28:29], v[94:95], v[26:27]
	v_pk_mul_f32 v[26:27], v[92:93], v[30:31]
	v_cvt_pk_bf16_f32 v24, v24, v25
	v_cvt_pk_bf16_f32 v25, v34, v35
	v_lshlrev_b32_e32 v34, 12, v32
	v_cvt_pk_bf16_f32 v26, v26, v27
	v_cvt_pk_bf16_f32 v27, v28, v29
	v_sub_u32_e32 v28, v36, v34
	global_store_dwordx4 v28, v[24:27], s[18:19] sc1
	v_lshlrev_b32_e32 v28, 16, v90
	v_and_b32_e32 v29, 0xffff0000, v90
	v_lshlrev_b32_e32 v24, 16, v88
	v_and_b32_e32 v25, 0xffff0000, v88
	v_lshlrev_b32_e32 v26, 16, v89
	v_and_b32_e32 v27, 0xffff0000, v89
	v_lshlrev_b32_e32 v30, 16, v91
	v_and_b32_e32 v31, 0xffff0000, v91
	v_pk_fma_f32 v[22:23], v[22:23], v[86:87], v[26:27]
	v_pk_fma_f32 v[20:21], v[20:21], v[84:85], v[24:25]
	v_pk_fma_f32 v[24:25], v[18:19], v[82:83], v[30:31]
	v_pk_fma_f32 v[18:19], v[16:17], v[80:81], v[28:29]
	v_cvt_pk_bf16_f32 v16, v20, v21
	v_cvt_pk_bf16_f32 v17, v22, v23
	v_add_u32_e32 v26, v144, v33
	v_cvt_pk_bf16_f32 v18, v18, v19
	v_cvt_pk_bf16_f32 v19, v24, v25
	global_store_dwordx4 v26, v[16:19], s[4:5]
	v_lshlrev_b32_e32 v20, 16, v16
	v_and_b32_e32 v21, 0xffff0000, v16
	v_lshlrev_b32_e32 v16, 16, v17
	v_and_b32_e32 v17, 0xffff0000, v17
	v_mul_f32_e32 v24, v21, v21
	v_mul_f32_e32 v25, v17, v17
	v_lshlrev_b32_e32 v22, 16, v18
	v_and_b32_e32 v23, 0xffff0000, v18
	v_lshlrev_b32_e32 v18, 16, v19
	v_and_b32_e32 v19, 0xffff0000, v19
	v_fmac_f32_e32 v24, v20, v20
	v_fmac_f32_e32 v25, v16, v16
	v_add_f32_e32 v24, v24, v25
	v_mul_f32_e32 v25, v23, v23
	v_mul_f32_e32 v27, v19, v19
	v_fmac_f32_e32 v25, v22, v22
	v_fmac_f32_e32 v27, v18, v18
	v_add_f32_e32 v25, v25, v27
	v_add_f32_e32 v24, v24, v25
	v_add_f32_e32 v27, v37, v24
	v_pk_mul_f32 v[24:25], v[78:79], v[16:17]
	v_pk_mul_f32 v[16:17], v[76:77], v[20:21]
	v_pk_mul_f32 v[20:21], v[70:71], v[18:19]
	v_pk_mul_f32 v[18:19], v[68:69], v[22:23]
	ds_swizzle_b32 v22, v27 offset:swizzle(SWAP,16)
	v_cvt_pk_bf16_f32 v16, v16, v17
	v_cvt_pk_bf16_f32 v17, v24, v25
	v_cvt_pk_bf16_f32 v18, v18, v19
	v_cvt_pk_bf16_f32 v19, v20, v21
	v_sub_u32_e32 v20, v26, v34
	global_store_dwordx4 v20, v[16:19], s[18:19] sc1
	s_waitcnt lgkmcnt(0)
	s_nop 0
	v_add_f32_e32 v16, v27, v22
	v_mov_b32_e32 v17, v16
	s_nop 1
	v_permlane32_swap_b32_e32 v16, v17
	s_and_saveexec_b64 s[86:87], vcc
	s_cbranch_execz .LBB0_982
	v_add_f32_e32 v16, v16, v17
	s_mov_b32 s3, 0x47800000
	v_fma_f32 v16, v16, s3, 0.5
	v_trunc_f32_e32 v16, v16
	v_mul_f32_e32 v17, 0x2f800000, v16
	v_floor_f32_e32 v17, v17
	v_fmac_f32_e32 v16, 0xcf800000, v17
	v_cvt_u32_f32_e32 v16, v16
	v_cvt_u32_f32_e32 v17, v17
	v_lshlrev_b32_e32 v18, 3, v32
	global_atomic_add_x2 v18, v[16:17], s[6:7]
.LBB0_982:
	s_or_b64 exec, exec, s[86:87]
	v_add_u32_e32 v16, 0xb0, v242
	v_lshlrev_b32_e32 v17, 13, v16
	v_lshlrev_b32_e32 v18, 16, v72
	v_and_b32_e32 v19, 0xffff0000, v72
	v_lshlrev_b32_e32 v20, 16, v73
	v_and_b32_e32 v21, 0xffff0000, v73
	v_lshlrev_b32_e32 v22, 16, v74
	v_and_b32_e32 v23, 0xffff0000, v74
	v_lshlrev_b32_e32 v24, 16, v75
	v_and_b32_e32 v25, 0xffff0000, v75
	v_pk_fma_f32 v[14:15], v[14:15], v[114:115], v[20:21]
	v_pk_fma_f32 v[12:13], v[12:13], v[112:113], v[18:19]
	v_pk_fma_f32 v[18:19], v[10:11], v[106:107], v[24:25]
	v_pk_fma_f32 v[10:11], v[8:9], v[104:105], v[22:23]
	v_cvt_pk_bf16_f32 v8, v12, v13
	v_cvt_pk_bf16_f32 v9, v14, v15
	v_add_u32_e32 v20, v241, v17
	v_cvt_pk_bf16_f32 v10, v10, v11
	v_cvt_pk_bf16_f32 v11, v18, v19
	global_store_dwordx4 v20, v[8:11], s[4:5]
	v_lshlrev_b32_e32 v12, 16, v8
	v_and_b32_e32 v13, 0xffff0000, v8
	v_lshlrev_b32_e32 v8, 16, v9
	v_and_b32_e32 v9, 0xffff0000, v9
	v_mul_f32_e32 v18, v13, v13
	v_mul_f32_e32 v19, v9, v9
	v_lshlrev_b32_e32 v14, 16, v10
	v_and_b32_e32 v15, 0xffff0000, v10
	v_lshlrev_b32_e32 v10, 16, v11
	v_and_b32_e32 v11, 0xffff0000, v11
	v_fmac_f32_e32 v18, v12, v12
	v_fmac_f32_e32 v19, v8, v8
	v_add_f32_e32 v18, v18, v19
	v_mul_f32_e32 v19, v15, v15
	v_mul_f32_e32 v21, v11, v11
	v_fmac_f32_e32 v19, v14, v14
	v_fmac_f32_e32 v21, v10, v10
	v_add_f32_e32 v19, v19, v21
	v_add_f32_e32 v21, v18, v19
	v_pk_mul_f32 v[18:19], v[102:103], v[8:9]
	v_pk_mul_f32 v[8:9], v[100:101], v[12:13]
	v_pk_mul_f32 v[12:13], v[94:95], v[10:11]
	v_pk_mul_f32 v[10:11], v[92:93], v[14:15]
	v_cvt_pk_bf16_f32 v8, v8, v9
	v_cvt_pk_bf16_f32 v9, v18, v19
	v_lshlrev_b32_e32 v18, 12, v16
	v_cvt_pk_bf16_f32 v10, v10, v11
	v_cvt_pk_bf16_f32 v11, v12, v13
	v_sub_u32_e32 v12, v20, v18
	global_store_dwordx4 v12, v[8:11], s[18:19] sc1
	v_lshlrev_b32_e32 v12, 16, v66
	v_and_b32_e32 v13, 0xffff0000, v66
	v_lshlrev_b32_e32 v8, 16, v64
	v_and_b32_e32 v9, 0xffff0000, v64
	v_lshlrev_b32_e32 v10, 16, v65
	v_and_b32_e32 v11, 0xffff0000, v65
	v_lshlrev_b32_e32 v14, 16, v67
	v_and_b32_e32 v15, 0xffff0000, v67
	v_pk_fma_f32 v[6:7], v[6:7], v[86:87], v[10:11]
	v_pk_fma_f32 v[4:5], v[4:5], v[84:85], v[8:9]
	v_pk_fma_f32 v[8:9], v[2:3], v[82:83], v[14:15]
	v_pk_fma_f32 v[2:3], v[0:1], v[80:81], v[12:13]
	v_cvt_pk_bf16_f32 v0, v4, v5
	v_cvt_pk_bf16_f32 v1, v6, v7
	v_add_u32_e32 v10, v144, v17
	v_cvt_pk_bf16_f32 v2, v2, v3
	v_cvt_pk_bf16_f32 v3, v8, v9
	global_store_dwordx4 v10, v[0:3], s[4:5]
	v_lshlrev_b32_e32 v4, 16, v0
	v_and_b32_e32 v5, 0xffff0000, v0
	v_lshlrev_b32_e32 v0, 16, v1
	v_and_b32_e32 v1, 0xffff0000, v1
	v_mul_f32_e32 v8, v5, v5
	v_mul_f32_e32 v9, v1, v1
	v_lshlrev_b32_e32 v6, 16, v2
	v_and_b32_e32 v7, 0xffff0000, v2
	v_lshlrev_b32_e32 v2, 16, v3
	v_and_b32_e32 v3, 0xffff0000, v3
	v_fmac_f32_e32 v8, v4, v4
	v_fmac_f32_e32 v9, v0, v0
	v_add_f32_e32 v8, v8, v9
	v_mul_f32_e32 v9, v7, v7
	v_mul_f32_e32 v11, v3, v3
	v_fmac_f32_e32 v9, v6, v6
	v_fmac_f32_e32 v11, v2, v2
	v_add_f32_e32 v9, v9, v11
	v_add_f32_e32 v8, v8, v9
	v_add_f32_e32 v11, v21, v8
	v_pk_mul_f32 v[8:9], v[78:79], v[0:1]
	v_pk_mul_f32 v[0:1], v[76:77], v[4:5]
	v_pk_mul_f32 v[4:5], v[70:71], v[2:3]
	v_pk_mul_f32 v[2:3], v[68:69], v[6:7]
	ds_swizzle_b32 v6, v11 offset:swizzle(SWAP,16)
	v_cvt_pk_bf16_f32 v0, v0, v1
	v_cvt_pk_bf16_f32 v1, v8, v9
	v_cvt_pk_bf16_f32 v2, v2, v3
	v_cvt_pk_bf16_f32 v3, v4, v5
	v_sub_u32_e32 v4, v10, v18
	global_store_dwordx4 v4, v[0:3], s[18:19] sc1
	s_waitcnt lgkmcnt(0)
	s_nop 0
	v_add_f32_e32 v0, v11, v6
	v_mov_b32_e32 v1, v0
	s_nop 1
	v_permlane32_swap_b32_e32 v0, v1
	s_and_saveexec_b64 s[86:87], vcc
	s_cbranch_execz .LBB0_984
	v_add_f32_e32 v0, v0, v1
	s_mov_b32 s3, 0x47800000
	v_fma_f32 v0, v0, s3, 0.5
	v_trunc_f32_e32 v0, v0
	v_mul_f32_e32 v1, 0x2f800000, v0
	v_floor_f32_e32 v1, v1
	v_fmac_f32_e32 v0, 0xcf800000, v1
	v_cvt_u32_f32_e32 v0, v0
	v_cvt_u32_f32_e32 v1, v1
	v_lshlrev_b32_e32 v2, 3, v16
	global_atomic_add_x2 v2, v[0:1], s[6:7]

.Lsk_epi:
	v_readlane_b32 s32, v255, 22
	v_mbcnt_lo_u32_b32 v64, -1, 0
	v_mbcnt_hi_u32_b32 v64, -1, v64
	s_add_i32 s95, s95, s39
	v_ashrrev_i32_e32 v65, 1, v64
	v_and_or_b32 v242, v64, 15, s95
	s_or_b32 s78, s80, s53
	v_and_b32_e32 v65, -8, v65
	v_lshlrev_b32_e32 v220, 13, v242
	v_add_lshl_u32 v241, s78, v65, 1
	v_add_u32_e32 v221, v241, v220
	global_load_dwordx4 v[244:247], v221, s[20:21]
	s_add_i32 s67, s67, s68
	v_cmp_gt_u32_e32 vcc, 16, v64
	v_add_lshl_u32 v64, v65, s53, 2
	v_add_u32_e32 v243, s67, v64
	v_add_u32_e32 v64, 0x100, v221
	global_load_dwordx4 v[248:251], v64, s[20:21]
	v_add_u32_e32 v65, 0x20000, v221
	v_add_u32_e32 v66, 0x20100, v221
	v_add_u32_e32 v67, 0x40000, v221
	v_add_u32_e32 v72, 0x40100, v221
	v_add_u32_e32 v64, 0x60000, v221
	v_add_u32_e32 v73, 0x60100, v221
	v_add_u32_e32 v74, 0x100000, v221
	v_add_u32_e32 v75, 0x100100, v221
	v_add_u32_e32 v88, 0x120000, v221
	v_add_u32_e32 v89, 0x120100, v221
	v_add_u32_e32 v90, 0x140000, v221
	v_add_u32_e32 v91, 0x140100, v221
	v_add_u32_e32 v152, 0x160000, v221
	v_add_u32_e32 v153, 0x160100, v221
	global_load_dwordx4 v[212:215], v65, s[20:21]
	global_load_dwordx4 v[208:211], v66, s[20:21]
	global_load_dwordx4 v[204:207], v67, s[20:21]
	global_load_dwordx4 v[200:203], v72, s[20:21]
	global_load_dwordx4 v[192:195], v64, s[20:21]
	global_load_dwordx4 v[164:167], v73, s[20:21]
	global_load_dwordx4 v[140:143], v74, s[20:21]
	global_load_dwordx4 v[128:131], v75, s[20:21]
	global_load_dwordx4 v[116:119], v88, s[20:21]
	global_load_dwordx4 v[108:111], v89, s[20:21]
	global_load_dwordx4 v[96:99], v90, s[20:21]
	s_nop 0
	global_load_dwordx4 v[88:91], v91, s[20:21]
	s_nop 0
	global_load_dwordx4 v[72:75], v152, s[20:21]
	global_load_dwordx4 v[64:67], v153, s[20:21]
	s_waitcnt vmcnt(0)
	ds_read_b128 v[196:199], v243
	ds_read_b128 v[188:191], v243 offset:16
	ds_read_b128 v[184:187], v243 offset:4096
	ds_read_b128 v[180:183], v243 offset:4112
	ds_read_b128 v[168:171], v243 offset:512
	ds_read_b128 v[160:163], v243 offset:528
	ds_read_b128 v[156:159], v243 offset:4608
	ds_read_b128 v[152:155], v243 offset:4624
	v_lshlrev_b32_e32 v235, 12, v242
	s_waitcnt vmcnt(0)
	v_lshlrev_b32_e32 v218, 16, v244
	v_and_b32_e32 v219, 0xffff0000, v244
	v_lshlrev_b32_e32 v252, 16, v246
	v_and_b32_e32 v253, 0xffff0000, v246
	v_lshlrev_b32_e32 v246, 16, v247
	v_and_b32_e32 v247, 0xffff0000, v247
	v_lshlrev_b32_e32 v244, 16, v245
	v_and_b32_e32 v245, 0xffff0000, v245
	s_waitcnt lgkmcnt(7)
	v_pk_fma_f32 v[176:177], v[176:177], v[196:197], v[218:219]
	s_waitcnt lgkmcnt(6)
	v_pk_fma_f32 v[218:219], v[174:175], v[190:191], v[246:247]
	v_pk_fma_f32 v[174:175], v[172:173], v[188:189], v[252:253]
	v_pk_fma_f32 v[178:179], v[178:179], v[198:199], v[244:245]
	v_cvt_pk_bf16_f32 v172, v176, v177
	s_nop 0
	v_cvt_pk_bf16_f32 v173, v178, v179
	v_cvt_pk_bf16_f32 v174, v174, v175
	v_cvt_pk_bf16_f32 v175, v218, v219
	global_store_dwordx4 v221, v[172:175], s[20:21]
	v_lshlrev_b32_e32 v176, 16, v172
	v_and_b32_e32 v177, 0xffff0000, v172
	v_lshlrev_b32_e32 v172, 16, v173
	v_and_b32_e32 v173, 0xffff0000, v173
	v_lshlrev_b32_e32 v178, 16, v174
	v_and_b32_e32 v179, 0xffff0000, v174
	v_lshlrev_b32_e32 v174, 16, v175
	v_and_b32_e32 v175, 0xffff0000, v175
	v_mul_f32_e32 v221, v177, v177
	v_mul_f32_e32 v236, v173, v173
	v_mul_f32_e32 v252, v179, v179
	v_mul_f32_e32 v253, v175, v175
	v_fmac_f32_e32 v221, v176, v176
	v_fmac_f32_e32 v236, v172, v172
	v_fmac_f32_e32 v252, v178, v178
	v_fmac_f32_e32 v253, v174, v174
	s_waitcnt lgkmcnt(5)
	v_pk_mul_f32 v[218:219], v[186:187], v[172:173]
	v_add_f32_e32 v172, v221, v236
	v_add_f32_e32 v173, v252, v253
	v_pk_mul_f32 v[244:245], v[184:185], v[176:177]
	s_waitcnt lgkmcnt(4)
	v_pk_mul_f32 v[246:247], v[182:183], v[174:175]
	v_add_f32_e32 v221, v172, v173
	v_pk_mul_f32 v[174:175], v[180:181], v[178:179]
	v_cvt_pk_bf16_f32 v172, v244, v245
	v_cvt_pk_bf16_f32 v173, v218, v219
	v_add_u32_e32 v176, v241, v235
	v_cvt_pk_bf16_f32 v174, v174, v175
	v_cvt_pk_bf16_f32 v175, v246, v247
	s_cmp_eq_u32 s32, 3
	s_cbranch_scc1 .Lxg3_0
	global_store_dwordx4 v176, v[172:175], s[22:23] sc1
.Lxg3_0:
	v_lshlrev_b32_e32 v176, 16, v250
	v_and_b32_e32 v177, 0xffff0000, v250
	v_lshlrev_b32_e32 v172, 16, v248
	v_and_b32_e32 v173, 0xffff0000, v248
	v_lshlrev_b32_e32 v174, 16, v249
	v_and_b32_e32 v175, 0xffff0000, v249
	v_lshlrev_b32_e32 v178, 16, v251
	v_and_b32_e32 v179, 0xffff0000, v251
	s_waitcnt lgkmcnt(3)
	v_pk_fma_f32 v[148:149], v[148:149], v[168:169], v[172:173]
	s_waitcnt lgkmcnt(2)
	v_pk_fma_f32 v[144:145], v[144:145], v[160:161], v[176:177]
	v_pk_fma_f32 v[150:151], v[150:151], v[170:171], v[174:175]
	v_pk_fma_f32 v[172:173], v[146:147], v[162:163], v[178:179]
	v_cvt_pk_bf16_f32 v146, v148, v149
	v_cvt_pk_bf16_f32 v147, v150, v151
	v_cvt_pk_bf16_f32 v148, v144, v145
	v_add_u32_e32 v144, 0x100, v241
	v_add_u32_e32 v145, v144, v220
	v_cvt_pk_bf16_f32 v149, v172, v173
	global_store_dwordx4 v145, v[146:149], s[20:21]
	v_lshlrev_b32_e32 v150, 16, v146
	v_and_b32_e32 v151, 0xffff0000, v146
	v_lshlrev_b32_e32 v146, 16, v147
	v_and_b32_e32 v147, 0xffff0000, v147
	v_mul_f32_e32 v174, v151, v151
	v_mul_f32_e32 v175, v147, v147
	v_lshlrev_b32_e32 v172, 16, v148
	v_and_b32_e32 v173, 0xffff0000, v148
	v_lshlrev_b32_e32 v148, 16, v149
	v_and_b32_e32 v149, 0xffff0000, v149
	v_fmac_f32_e32 v174, v150, v150
	v_fmac_f32_e32 v175, v146, v146
	v_add_f32_e32 v174, v174, v175
	v_mul_f32_e32 v175, v173, v173
	v_mul_f32_e32 v176, v149, v149
	v_fmac_f32_e32 v175, v172, v172
	v_fmac_f32_e32 v176, v148, v148
	v_add_f32_e32 v175, v175, v176
	v_add_f32_e32 v174, v174, v175
	v_add_f32_e32 v176, v221, v174
	s_waitcnt lgkmcnt(1)
	v_pk_mul_f32 v[174:175], v[158:159], v[146:147]
	v_pk_mul_f32 v[146:147], v[156:157], v[150:151]
	s_waitcnt lgkmcnt(0)
	v_pk_mul_f32 v[150:151], v[154:155], v[148:149]
	v_pk_mul_f32 v[148:149], v[152:153], v[172:173]
	ds_swizzle_b32 v172, v176 offset:swizzle(SWAP,16)
	v_sub_u32_e32 v145, v145, v235
	v_cvt_pk_bf16_f32 v146, v146, v147
	v_cvt_pk_bf16_f32 v147, v174, v175
	v_cvt_pk_bf16_f32 v148, v148, v149
	v_cvt_pk_bf16_f32 v149, v150, v151
	s_cmp_eq_u32 s32, 3
	s_cbranch_scc1 .Lxg3_1
	global_store_dwordx4 v145, v[146:149], s[22:23] sc1

.LBB0_1295:
	s_or_b64 exec, exec, s[78:79]
	v_or_b32_e32 v145, 16, v242
	v_lshlrev_b32_e32 v174, 13, v145
	v_lshlrev_b32_e32 v146, 16, v212
	v_and_b32_e32 v147, 0xffff0000, v212
	v_lshlrev_b32_e32 v148, 16, v213
	v_and_b32_e32 v149, 0xffff0000, v213
	v_lshlrev_b32_e32 v150, 16, v214
	v_and_b32_e32 v151, 0xffff0000, v214
	v_lshlrev_b32_e32 v172, 16, v215
	v_and_b32_e32 v173, 0xffff0000, v215
	v_pk_fma_f32 v[138:139], v[138:139], v[198:199], v[148:149]
	v_pk_fma_f32 v[136:137], v[136:137], v[196:197], v[146:147]
	v_pk_fma_f32 v[146:147], v[134:135], v[190:191], v[172:173]
	v_pk_fma_f32 v[134:135], v[132:133], v[188:189], v[150:151]
	v_cvt_pk_bf16_f32 v132, v136, v137
	v_cvt_pk_bf16_f32 v133, v138, v139
	v_add_u32_e32 v148, v241, v174
	v_cvt_pk_bf16_f32 v134, v134, v135
	v_cvt_pk_bf16_f32 v135, v146, v147
	global_store_dwordx4 v148, v[132:135], s[20:21]
	v_lshlrev_b32_e32 v136, 16, v132
	v_and_b32_e32 v137, 0xffff0000, v132
	v_lshlrev_b32_e32 v132, 16, v133
	v_and_b32_e32 v133, 0xffff0000, v133
	v_mul_f32_e32 v146, v137, v137
	v_mul_f32_e32 v147, v133, v133
	v_lshlrev_b32_e32 v138, 16, v134
	v_and_b32_e32 v139, 0xffff0000, v134
	v_lshlrev_b32_e32 v134, 16, v135
	v_and_b32_e32 v135, 0xffff0000, v135
	v_fmac_f32_e32 v146, v136, v136
	v_fmac_f32_e32 v147, v132, v132
	v_add_f32_e32 v146, v146, v147
	v_mul_f32_e32 v147, v139, v139
	v_mul_f32_e32 v149, v135, v135
	v_fmac_f32_e32 v147, v138, v138
	v_fmac_f32_e32 v149, v134, v134
	v_add_f32_e32 v147, v147, v149
	v_add_f32_e32 v149, v146, v147
	v_pk_mul_f32 v[146:147], v[186:187], v[132:133]
	v_pk_mul_f32 v[132:133], v[184:185], v[136:137]
	v_pk_mul_f32 v[136:137], v[182:183], v[134:135]
	v_pk_mul_f32 v[134:135], v[180:181], v[138:139]
	v_cvt_pk_bf16_f32 v132, v132, v133
	v_cvt_pk_bf16_f32 v133, v146, v147
	v_lshlrev_b32_e32 v146, 12, v145
	v_cvt_pk_bf16_f32 v134, v134, v135
	v_cvt_pk_bf16_f32 v135, v136, v137
	v_sub_u32_e32 v136, v148, v146
	s_cmp_eq_u32 s32, 3
	s_cbranch_scc1 .Lxg3_2
	global_store_dwordx4 v136, v[132:135], s[22:23] sc1
.Lxg3_2:
	v_lshlrev_b32_e32 v136, 16, v210
	v_and_b32_e32 v137, 0xffff0000, v210
	v_lshlrev_b32_e32 v132, 16, v208
	v_and_b32_e32 v133, 0xffff0000, v208
	v_lshlrev_b32_e32 v134, 16, v209
	v_and_b32_e32 v135, 0xffff0000, v209
	v_lshlrev_b32_e32 v138, 16, v211
	v_and_b32_e32 v139, 0xffff0000, v211
	v_pk_fma_f32 v[126:127], v[126:127], v[170:171], v[134:135]
	v_pk_fma_f32 v[124:125], v[124:125], v[168:169], v[132:133]
	v_pk_fma_f32 v[132:133], v[122:123], v[162:163], v[138:139]
	v_pk_fma_f32 v[122:123], v[120:121], v[160:161], v[136:137]
	v_cvt_pk_bf16_f32 v120, v124, v125
	v_cvt_pk_bf16_f32 v121, v126, v127
	v_add_u32_e32 v134, v144, v174
	v_cvt_pk_bf16_f32 v122, v122, v123
	v_cvt_pk_bf16_f32 v123, v132, v133
	global_store_dwordx4 v134, v[120:123], s[20:21]
	v_lshlrev_b32_e32 v124, 16, v120
	v_and_b32_e32 v125, 0xffff0000, v120
	v_lshlrev_b32_e32 v120, 16, v121
	v_and_b32_e32 v121, 0xffff0000, v121
	v_mul_f32_e32 v132, v125, v125
	v_mul_f32_e32 v133, v121, v121
	v_lshlrev_b32_e32 v126, 16, v122
	v_and_b32_e32 v127, 0xffff0000, v122
	v_lshlrev_b32_e32 v122, 16, v123
	v_and_b32_e32 v123, 0xffff0000, v123
	v_fmac_f32_e32 v132, v124, v124
	v_fmac_f32_e32 v133, v120, v120
	v_add_f32_e32 v132, v132, v133
	v_mul_f32_e32 v133, v127, v127
	v_mul_f32_e32 v135, v123, v123
	v_fmac_f32_e32 v133, v126, v126
	v_fmac_f32_e32 v135, v122, v122
	v_add_f32_e32 v133, v133, v135
	v_add_f32_e32 v132, v132, v133
	v_add_f32_e32 v135, v149, v132
	v_pk_mul_f32 v[132:133], v[158:159], v[120:121]
	v_pk_mul_f32 v[120:121], v[156:157], v[124:125]
	v_pk_mul_f32 v[124:125], v[154:155], v[122:123]
	v_pk_mul_f32 v[122:123], v[152:153], v[126:127]
	ds_swizzle_b32 v126, v135 offset:swizzle(SWAP,16)
	v_cvt_pk_bf16_f32 v120, v120, v121
	v_cvt_pk_bf16_f32 v121, v132, v133
	v_cvt_pk_bf16_f32 v122, v122, v123
	v_cvt_pk_bf16_f32 v123, v124, v125
	v_sub_u32_e32 v124, v134, v146
	s_cmp_eq_u32 s32, 3
	s_cbranch_scc1 .Lxg3_3
	global_store_dwordx4 v124, v[120:123], s[22:23] sc1

.LBB0_1297:
	s_or_b64 exec, exec, s[78:79]
	v_or_b32_e32 v120, 32, v242
	v_lshlrev_b32_e32 v121, 13, v120
	v_lshlrev_b32_e32 v122, 16, v204
	v_and_b32_e32 v123, 0xffff0000, v204
	v_lshlrev_b32_e32 v124, 16, v205
	v_and_b32_e32 v125, 0xffff0000, v205
	v_lshlrev_b32_e32 v126, 16, v206
	v_and_b32_e32 v127, 0xffff0000, v206
	v_lshlrev_b32_e32 v132, 16, v207
	v_and_b32_e32 v133, 0xffff0000, v207
	v_pk_fma_f32 v[114:115], v[114:115], v[198:199], v[124:125]
	v_pk_fma_f32 v[112:113], v[112:113], v[196:197], v[122:123]
	v_pk_fma_f32 v[122:123], v[106:107], v[190:191], v[132:133]
	v_pk_fma_f32 v[106:107], v[104:105], v[188:189], v[126:127]
	v_cvt_pk_bf16_f32 v104, v112, v113
	v_cvt_pk_bf16_f32 v105, v114, v115
	v_add_u32_e32 v124, v241, v121
	v_cvt_pk_bf16_f32 v106, v106, v107
	v_cvt_pk_bf16_f32 v107, v122, v123
	global_store_dwordx4 v124, v[104:107], s[20:21]
	v_lshlrev_b32_e32 v112, 16, v104
	v_and_b32_e32 v113, 0xffff0000, v104
	v_lshlrev_b32_e32 v104, 16, v105
	v_and_b32_e32 v105, 0xffff0000, v105
	v_mul_f32_e32 v122, v113, v113
	v_mul_f32_e32 v123, v105, v105
	v_lshlrev_b32_e32 v114, 16, v106
	v_and_b32_e32 v115, 0xffff0000, v106
	v_lshlrev_b32_e32 v106, 16, v107
	v_and_b32_e32 v107, 0xffff0000, v107
	v_fmac_f32_e32 v122, v112, v112
	v_fmac_f32_e32 v123, v104, v104
	v_add_f32_e32 v122, v122, v123
	v_mul_f32_e32 v123, v115, v115
	v_mul_f32_e32 v125, v107, v107
	v_fmac_f32_e32 v123, v114, v114
	v_fmac_f32_e32 v125, v106, v106
	v_add_f32_e32 v123, v123, v125
	v_add_f32_e32 v125, v122, v123
	v_pk_mul_f32 v[122:123], v[186:187], v[104:105]
	v_pk_mul_f32 v[104:105], v[184:185], v[112:113]
	v_pk_mul_f32 v[112:113], v[182:183], v[106:107]
	v_pk_mul_f32 v[106:107], v[180:181], v[114:115]
	v_cvt_pk_bf16_f32 v104, v104, v105
	v_cvt_pk_bf16_f32 v105, v122, v123
	v_lshlrev_b32_e32 v122, 12, v120
	v_cvt_pk_bf16_f32 v106, v106, v107
	v_cvt_pk_bf16_f32 v107, v112, v113
	v_sub_u32_e32 v112, v124, v122
	s_cmp_eq_u32 s32, 3
	s_cbranch_scc1 .Lxg3_4
	global_store_dwordx4 v112, v[104:107], s[22:23] sc1
.Lxg3_4:
	v_lshlrev_b32_e32 v112, 16, v202
	v_and_b32_e32 v113, 0xffff0000, v202
	v_lshlrev_b32_e32 v104, 16, v200
	v_and_b32_e32 v105, 0xffff0000, v200
	v_lshlrev_b32_e32 v106, 16, v201
	v_and_b32_e32 v107, 0xffff0000, v201
	v_lshlrev_b32_e32 v114, 16, v203
	v_and_b32_e32 v115, 0xffff0000, v203
	v_pk_fma_f32 v[102:103], v[102:103], v[170:171], v[106:107]
	v_pk_fma_f32 v[100:101], v[100:101], v[168:169], v[104:105]
	v_pk_fma_f32 v[104:105], v[94:95], v[162:163], v[114:115]
	v_pk_fma_f32 v[94:95], v[92:93], v[160:161], v[112:113]
	v_cvt_pk_bf16_f32 v92, v100, v101
	v_cvt_pk_bf16_f32 v93, v102, v103
	v_add_u32_e32 v106, v144, v121
	v_cvt_pk_bf16_f32 v94, v94, v95
	v_cvt_pk_bf16_f32 v95, v104, v105
	global_store_dwordx4 v106, v[92:95], s[20:21]
	v_lshlrev_b32_e32 v100, 16, v92
	v_and_b32_e32 v101, 0xffff0000, v92
	v_lshlrev_b32_e32 v92, 16, v93
	v_and_b32_e32 v93, 0xffff0000, v93
	v_mul_f32_e32 v104, v101, v101
	v_mul_f32_e32 v105, v93, v93
	v_lshlrev_b32_e32 v102, 16, v94
	v_and_b32_e32 v103, 0xffff0000, v94
	v_lshlrev_b32_e32 v94, 16, v95
	v_and_b32_e32 v95, 0xffff0000, v95
	v_fmac_f32_e32 v104, v100, v100
	v_fmac_f32_e32 v105, v92, v92
	v_add_f32_e32 v104, v104, v105
	v_mul_f32_e32 v105, v103, v103
	v_mul_f32_e32 v107, v95, v95
	v_fmac_f32_e32 v105, v102, v102
	v_fmac_f32_e32 v107, v94, v94
	v_add_f32_e32 v105, v105, v107
	v_add_f32_e32 v104, v104, v105
	v_add_f32_e32 v107, v125, v104
	v_pk_mul_f32 v[104:105], v[158:159], v[92:93]
	v_pk_mul_f32 v[92:93], v[156:157], v[100:101]
	v_pk_mul_f32 v[100:101], v[154:155], v[94:95]
	v_pk_mul_f32 v[94:95], v[152:153], v[102:103]
	ds_swizzle_b32 v102, v107 offset:swizzle(SWAP,16)
	v_cvt_pk_bf16_f32 v92, v92, v93
	v_cvt_pk_bf16_f32 v93, v104, v105
	v_cvt_pk_bf16_f32 v94, v94, v95
	v_cvt_pk_bf16_f32 v95, v100, v101
	v_sub_u32_e32 v100, v106, v122
	s_cmp_eq_u32 s32, 3
	s_cbranch_scc1 .Lxg3_5
	global_store_dwordx4 v100, v[92:95], s[22:23] sc1

.LBB0_1299:
	s_or_b64 exec, exec, s[78:79]
	v_or_b32_e32 v92, 48, v242
	v_lshlrev_b32_e32 v93, 13, v92
	v_lshlrev_b32_e32 v94, 16, v192
	v_and_b32_e32 v95, 0xffff0000, v192
	v_lshlrev_b32_e32 v100, 16, v193
	v_and_b32_e32 v101, 0xffff0000, v193
	v_lshlrev_b32_e32 v102, 16, v194
	v_and_b32_e32 v103, 0xffff0000, v194
	v_lshlrev_b32_e32 v104, 16, v195
	v_and_b32_e32 v105, 0xffff0000, v195
	v_pk_fma_f32 v[86:87], v[86:87], v[198:199], v[100:101]
	v_pk_fma_f32 v[84:85], v[84:85], v[196:197], v[94:95]
	v_pk_fma_f32 v[94:95], v[82:83], v[190:191], v[104:105]
	v_pk_fma_f32 v[82:83], v[80:81], v[188:189], v[102:103]
	v_cvt_pk_bf16_f32 v80, v84, v85
	v_cvt_pk_bf16_f32 v81, v86, v87
	v_add_u32_e32 v100, v241, v93
	v_cvt_pk_bf16_f32 v82, v82, v83
	v_cvt_pk_bf16_f32 v83, v94, v95
	global_store_dwordx4 v100, v[80:83], s[20:21]
	v_lshlrev_b32_e32 v84, 16, v80
	v_and_b32_e32 v85, 0xffff0000, v80
	v_lshlrev_b32_e32 v80, 16, v81
	v_and_b32_e32 v81, 0xffff0000, v81
	v_mul_f32_e32 v94, v85, v85
	v_mul_f32_e32 v95, v81, v81
	v_lshlrev_b32_e32 v86, 16, v82
	v_and_b32_e32 v87, 0xffff0000, v82
	v_lshlrev_b32_e32 v82, 16, v83
	v_and_b32_e32 v83, 0xffff0000, v83
	v_fmac_f32_e32 v94, v84, v84
	v_fmac_f32_e32 v95, v80, v80
	v_add_f32_e32 v94, v94, v95
	v_mul_f32_e32 v95, v87, v87
	v_mul_f32_e32 v101, v83, v83
	v_fmac_f32_e32 v95, v86, v86
	v_fmac_f32_e32 v101, v82, v82
	v_add_f32_e32 v95, v95, v101
	v_add_f32_e32 v101, v94, v95
	v_pk_mul_f32 v[94:95], v[186:187], v[80:81]
	v_pk_mul_f32 v[80:81], v[184:185], v[84:85]
	v_pk_mul_f32 v[84:85], v[182:183], v[82:83]
	v_pk_mul_f32 v[82:83], v[180:181], v[86:87]
	v_cvt_pk_bf16_f32 v80, v80, v81
	v_cvt_pk_bf16_f32 v81, v94, v95
	v_lshlrev_b32_e32 v94, 12, v92
	v_cvt_pk_bf16_f32 v82, v82, v83
	v_cvt_pk_bf16_f32 v83, v84, v85
	v_sub_u32_e32 v84, v100, v94
	s_cmp_eq_u32 s32, 3
	s_cbranch_scc1 .Lxg3_6
	global_store_dwordx4 v84, v[80:83], s[22:23] sc1
.Lxg3_6:
	v_lshlrev_b32_e32 v84, 16, v166
	v_and_b32_e32 v85, 0xffff0000, v166
	v_lshlrev_b32_e32 v80, 16, v164
	v_and_b32_e32 v81, 0xffff0000, v164
	v_lshlrev_b32_e32 v82, 16, v165
	v_and_b32_e32 v83, 0xffff0000, v165
	v_lshlrev_b32_e32 v86, 16, v167
	v_and_b32_e32 v87, 0xffff0000, v167
	v_pk_fma_f32 v[78:79], v[78:79], v[170:171], v[82:83]
	v_pk_fma_f32 v[76:77], v[76:77], v[168:169], v[80:81]
	v_pk_fma_f32 v[80:81], v[70:71], v[162:163], v[86:87]
	v_pk_fma_f32 v[70:71], v[68:69], v[160:161], v[84:85]
	v_cvt_pk_bf16_f32 v68, v76, v77
	v_cvt_pk_bf16_f32 v69, v78, v79
	v_add_u32_e32 v82, v144, v93
	v_cvt_pk_bf16_f32 v70, v70, v71
	v_cvt_pk_bf16_f32 v71, v80, v81
	global_store_dwordx4 v82, v[68:71], s[20:21]
	v_lshlrev_b32_e32 v76, 16, v68
	v_and_b32_e32 v77, 0xffff0000, v68
	v_lshlrev_b32_e32 v68, 16, v69
	v_and_b32_e32 v69, 0xffff0000, v69
	v_mul_f32_e32 v80, v77, v77
	v_mul_f32_e32 v81, v69, v69
	v_lshlrev_b32_e32 v78, 16, v70
	v_and_b32_e32 v79, 0xffff0000, v70
	v_lshlrev_b32_e32 v70, 16, v71
	v_and_b32_e32 v71, 0xffff0000, v71
	v_fmac_f32_e32 v80, v76, v76
	v_fmac_f32_e32 v81, v68, v68
	v_add_f32_e32 v80, v80, v81
	v_mul_f32_e32 v81, v79, v79
	v_mul_f32_e32 v83, v71, v71
	v_fmac_f32_e32 v81, v78, v78
	v_fmac_f32_e32 v83, v70, v70
	v_add_f32_e32 v81, v81, v83
	v_add_f32_e32 v80, v80, v81
	v_add_f32_e32 v83, v101, v80
	v_pk_mul_f32 v[80:81], v[158:159], v[68:69]
	v_pk_mul_f32 v[68:69], v[156:157], v[76:77]
	v_pk_mul_f32 v[76:77], v[154:155], v[70:71]
	v_pk_mul_f32 v[70:71], v[152:153], v[78:79]
	ds_swizzle_b32 v78, v83 offset:swizzle(SWAP,16)
	v_cvt_pk_bf16_f32 v68, v68, v69
	v_cvt_pk_bf16_f32 v69, v80, v81
	v_cvt_pk_bf16_f32 v70, v70, v71
	v_cvt_pk_bf16_f32 v71, v76, v77
	v_sub_u32_e32 v76, v82, v94
	s_cmp_eq_u32 s32, 3
	s_cbranch_scc1 .Lxg3_7
	global_store_dwordx4 v76, v[68:71], s[22:23] sc1

.LBB0_1301:
	s_or_b64 exec, exec, s[78:79]
	v_add_u32_e32 v120, 0x80, v242
	v_lshlrev_b32_e32 v121, 13, v120
	v_lshlrev_b32_e32 v122, 16, v140
	v_and_b32_e32 v123, 0xffff0000, v140
	v_lshlrev_b32_e32 v124, 16, v141
	v_and_b32_e32 v125, 0xffff0000, v141
	v_lshlrev_b32_e32 v126, 16, v142
	v_and_b32_e32 v127, 0xffff0000, v142
	v_lshlrev_b32_e32 v132, 16, v143
	v_and_b32_e32 v133, 0xffff0000, v143
	ds_read_b128 v[112:115], v243 offset:2048
	ds_read_b128 v[104:107], v243 offset:2064
	ds_read_b128 v[100:103], v243 offset:6144
	ds_read_b128 v[92:95], v243 offset:6160
	ds_read_b128 v[84:87], v243 offset:2560
	ds_read_b128 v[80:83], v243 offset:2576
	ds_read_b128 v[76:79], v243 offset:6656
	ds_read_b128 v[68:71], v243 offset:6672
	s_waitcnt lgkmcnt(7)
	v_pk_fma_f32 v[62:63], v[62:63], v[114:115], v[124:125]
	v_pk_fma_f32 v[60:61], v[60:61], v[112:113], v[122:123]
	s_waitcnt lgkmcnt(6)
	v_pk_fma_f32 v[122:123], v[58:59], v[106:107], v[132:133]
	v_pk_fma_f32 v[58:59], v[56:57], v[104:105], v[126:127]
	v_cvt_pk_bf16_f32 v56, v60, v61
	v_cvt_pk_bf16_f32 v57, v62, v63
	v_add_u32_e32 v124, v241, v121
	v_cvt_pk_bf16_f32 v58, v58, v59
	v_cvt_pk_bf16_f32 v59, v122, v123
	global_store_dwordx4 v124, v[56:59], s[20:21]
	v_lshlrev_b32_e32 v60, 16, v56
	v_and_b32_e32 v61, 0xffff0000, v56
	v_lshlrev_b32_e32 v56, 16, v57
	v_and_b32_e32 v57, 0xffff0000, v57
	v_mul_f32_e32 v122, v61, v61
	v_mul_f32_e32 v123, v57, v57
	v_lshlrev_b32_e32 v62, 16, v58
	v_and_b32_e32 v63, 0xffff0000, v58
	v_lshlrev_b32_e32 v58, 16, v59
	v_and_b32_e32 v59, 0xffff0000, v59
	v_fmac_f32_e32 v122, v60, v60
	v_fmac_f32_e32 v123, v56, v56
	v_add_f32_e32 v122, v122, v123
	v_mul_f32_e32 v123, v63, v63
	v_mul_f32_e32 v125, v59, v59
	v_fmac_f32_e32 v123, v62, v62
	v_fmac_f32_e32 v125, v58, v58
	v_add_f32_e32 v123, v123, v125
	v_add_f32_e32 v125, v122, v123
	s_waitcnt lgkmcnt(5)
	v_pk_mul_f32 v[122:123], v[102:103], v[56:57]
	v_pk_mul_f32 v[56:57], v[100:101], v[60:61]
	s_waitcnt lgkmcnt(4)
	v_pk_mul_f32 v[60:61], v[94:95], v[58:59]
	v_pk_mul_f32 v[58:59], v[92:93], v[62:63]
	v_cvt_pk_bf16_f32 v56, v56, v57
	v_cvt_pk_bf16_f32 v57, v122, v123
	v_lshlrev_b32_e32 v122, 12, v120
	v_cvt_pk_bf16_f32 v58, v58, v59
	v_cvt_pk_bf16_f32 v59, v60, v61
	v_sub_u32_e32 v60, v124, v122
	s_cmp_eq_u32 s32, 3
	s_cbranch_scc1 .Lxg3_8
	global_store_dwordx4 v60, v[56:59], s[22:23] sc1
.Lxg3_8:
	v_lshlrev_b32_e32 v60, 16, v130
	v_and_b32_e32 v61, 0xffff0000, v130
	v_lshlrev_b32_e32 v56, 16, v128
	v_and_b32_e32 v57, 0xffff0000, v128
	v_lshlrev_b32_e32 v58, 16, v129
	v_and_b32_e32 v59, 0xffff0000, v129
	v_lshlrev_b32_e32 v62, 16, v131
	v_and_b32_e32 v63, 0xffff0000, v131
	s_waitcnt lgkmcnt(3)
	v_pk_fma_f32 v[54:55], v[54:55], v[86:87], v[58:59]
	v_pk_fma_f32 v[52:53], v[52:53], v[84:85], v[56:57]
	s_waitcnt lgkmcnt(2)
	v_pk_fma_f32 v[56:57], v[50:51], v[82:83], v[62:63]
	v_pk_fma_f32 v[50:51], v[48:49], v[80:81], v[60:61]
	v_cvt_pk_bf16_f32 v48, v52, v53
	v_cvt_pk_bf16_f32 v49, v54, v55
	v_add_u32_e32 v58, v144, v121
	v_cvt_pk_bf16_f32 v50, v50, v51
	v_cvt_pk_bf16_f32 v51, v56, v57
	global_store_dwordx4 v58, v[48:51], s[20:21]
	v_lshlrev_b32_e32 v52, 16, v48
	v_and_b32_e32 v53, 0xffff0000, v48
	v_lshlrev_b32_e32 v48, 16, v49
	v_and_b32_e32 v49, 0xffff0000, v49
	v_mul_f32_e32 v56, v53, v53
	v_mul_f32_e32 v57, v49, v49
	v_lshlrev_b32_e32 v54, 16, v50
	v_and_b32_e32 v55, 0xffff0000, v50
	v_lshlrev_b32_e32 v50, 16, v51
	v_and_b32_e32 v51, 0xffff0000, v51
	v_fmac_f32_e32 v56, v52, v52
	v_fmac_f32_e32 v57, v48, v48
	v_add_f32_e32 v56, v56, v57
	v_mul_f32_e32 v57, v55, v55
	v_mul_f32_e32 v59, v51, v51
	v_fmac_f32_e32 v57, v54, v54
	v_fmac_f32_e32 v59, v50, v50
	v_add_f32_e32 v57, v57, v59
	v_add_f32_e32 v56, v56, v57
	v_add_f32_e32 v59, v125, v56
	s_waitcnt lgkmcnt(1)
	v_pk_mul_f32 v[56:57], v[78:79], v[48:49]
	v_pk_mul_f32 v[48:49], v[76:77], v[52:53]
	s_waitcnt lgkmcnt(0)
	v_pk_mul_f32 v[52:53], v[70:71], v[50:51]
	v_pk_mul_f32 v[50:51], v[68:69], v[54:55]
	ds_swizzle_b32 v54, v59 offset:swizzle(SWAP,16)
	v_cvt_pk_bf16_f32 v48, v48, v49
	v_cvt_pk_bf16_f32 v49, v56, v57
	v_cvt_pk_bf16_f32 v50, v50, v51
	v_cvt_pk_bf16_f32 v51, v52, v53
	v_sub_u32_e32 v52, v58, v122
	s_cmp_eq_u32 s32, 3
	s_cbranch_scc1 .Lxg3_9
	global_store_dwordx4 v52, v[48:51], s[22:23] sc1

.LBB0_1303:
	s_or_b64 exec, exec, s[78:79]
	v_add_u32_e32 v48, 0x90, v242
	v_lshlrev_b32_e32 v49, 13, v48
	v_lshlrev_b32_e32 v50, 16, v116
	v_and_b32_e32 v51, 0xffff0000, v116
	v_lshlrev_b32_e32 v52, 16, v117
	v_and_b32_e32 v53, 0xffff0000, v117
	v_lshlrev_b32_e32 v54, 16, v118
	v_and_b32_e32 v55, 0xffff0000, v118
	v_lshlrev_b32_e32 v56, 16, v119
	v_and_b32_e32 v57, 0xffff0000, v119
	v_pk_fma_f32 v[46:47], v[46:47], v[114:115], v[52:53]
	v_pk_fma_f32 v[44:45], v[44:45], v[112:113], v[50:51]
	v_pk_fma_f32 v[50:51], v[42:43], v[106:107], v[56:57]
	v_pk_fma_f32 v[42:43], v[40:41], v[104:105], v[54:55]
	v_cvt_pk_bf16_f32 v40, v44, v45
	v_cvt_pk_bf16_f32 v41, v46, v47
	v_add_u32_e32 v52, v241, v49
	v_cvt_pk_bf16_f32 v42, v42, v43
	v_cvt_pk_bf16_f32 v43, v50, v51
	global_store_dwordx4 v52, v[40:43], s[20:21]
	v_lshlrev_b32_e32 v44, 16, v40
	v_and_b32_e32 v45, 0xffff0000, v40
	v_lshlrev_b32_e32 v40, 16, v41
	v_and_b32_e32 v41, 0xffff0000, v41
	v_mul_f32_e32 v50, v45, v45
	v_mul_f32_e32 v51, v41, v41
	v_lshlrev_b32_e32 v46, 16, v42
	v_and_b32_e32 v47, 0xffff0000, v42
	v_lshlrev_b32_e32 v42, 16, v43
	v_and_b32_e32 v43, 0xffff0000, v43
	v_fmac_f32_e32 v50, v44, v44
	v_fmac_f32_e32 v51, v40, v40
	v_add_f32_e32 v50, v50, v51
	v_mul_f32_e32 v51, v47, v47
	v_mul_f32_e32 v53, v43, v43
	v_fmac_f32_e32 v51, v46, v46
	v_fmac_f32_e32 v53, v42, v42
	v_add_f32_e32 v51, v51, v53
	v_add_f32_e32 v53, v50, v51
	v_pk_mul_f32 v[50:51], v[102:103], v[40:41]
	v_pk_mul_f32 v[40:41], v[100:101], v[44:45]
	v_pk_mul_f32 v[44:45], v[94:95], v[42:43]
	v_pk_mul_f32 v[42:43], v[92:93], v[46:47]
	v_cvt_pk_bf16_f32 v40, v40, v41
	v_cvt_pk_bf16_f32 v41, v50, v51
	v_lshlrev_b32_e32 v50, 12, v48
	v_cvt_pk_bf16_f32 v42, v42, v43
	v_cvt_pk_bf16_f32 v43, v44, v45
	v_sub_u32_e32 v44, v52, v50
	s_cmp_eq_u32 s32, 3
	s_cbranch_scc1 .Lxg3_10
	global_store_dwordx4 v44, v[40:43], s[22:23] sc1
.Lxg3_10:
	v_lshlrev_b32_e32 v44, 16, v110
	v_and_b32_e32 v45, 0xffff0000, v110
	v_lshlrev_b32_e32 v40, 16, v108
	v_and_b32_e32 v41, 0xffff0000, v108
	v_lshlrev_b32_e32 v42, 16, v109
	v_and_b32_e32 v43, 0xffff0000, v109
	v_lshlrev_b32_e32 v46, 16, v111
	v_and_b32_e32 v47, 0xffff0000, v111
	v_pk_fma_f32 v[38:39], v[38:39], v[86:87], v[42:43]
	v_pk_fma_f32 v[36:37], v[36:37], v[84:85], v[40:41]
	v_pk_fma_f32 v[40:41], v[34:35], v[82:83], v[46:47]
	v_pk_fma_f32 v[34:35], v[32:33], v[80:81], v[44:45]
	v_cvt_pk_bf16_f32 v32, v36, v37
	v_cvt_pk_bf16_f32 v33, v38, v39
	v_add_u32_e32 v42, v144, v49
	v_cvt_pk_bf16_f32 v34, v34, v35
	v_cvt_pk_bf16_f32 v35, v40, v41
	global_store_dwordx4 v42, v[32:35], s[20:21]
	v_lshlrev_b32_e32 v36, 16, v32
	v_and_b32_e32 v37, 0xffff0000, v32
	v_lshlrev_b32_e32 v32, 16, v33
	v_and_b32_e32 v33, 0xffff0000, v33
	v_mul_f32_e32 v40, v37, v37
	v_mul_f32_e32 v41, v33, v33
	v_lshlrev_b32_e32 v38, 16, v34
	v_and_b32_e32 v39, 0xffff0000, v34
	v_lshlrev_b32_e32 v34, 16, v35
	v_and_b32_e32 v35, 0xffff0000, v35
	v_fmac_f32_e32 v40, v36, v36
	v_fmac_f32_e32 v41, v32, v32
	v_add_f32_e32 v40, v40, v41
	v_mul_f32_e32 v41, v39, v39
	v_mul_f32_e32 v43, v35, v35
	v_fmac_f32_e32 v41, v38, v38
	v_fmac_f32_e32 v43, v34, v34
	v_add_f32_e32 v41, v41, v43
	v_add_f32_e32 v40, v40, v41
	v_add_f32_e32 v43, v53, v40
	v_pk_mul_f32 v[40:41], v[78:79], v[32:33]
	v_pk_mul_f32 v[32:33], v[76:77], v[36:37]
	v_pk_mul_f32 v[36:37], v[70:71], v[34:35]
	v_pk_mul_f32 v[34:35], v[68:69], v[38:39]
	ds_swizzle_b32 v38, v43 offset:swizzle(SWAP,16)
	v_cvt_pk_bf16_f32 v32, v32, v33
	v_cvt_pk_bf16_f32 v33, v40, v41
	v_cvt_pk_bf16_f32 v34, v34, v35
	v_cvt_pk_bf16_f32 v35, v36, v37
	v_sub_u32_e32 v36, v42, v50
	s_cmp_eq_u32 s32, 3
	s_cbranch_scc1 .Lxg3_11
	global_store_dwordx4 v36, v[32:35], s[22:23] sc1

.LBB0_1305:
	s_or_b64 exec, exec, s[78:79]
	v_add_u32_e32 v32, 0xa0, v242
	v_lshlrev_b32_e32 v33, 13, v32
	v_lshlrev_b32_e32 v34, 16, v96
	v_and_b32_e32 v35, 0xffff0000, v96
	v_lshlrev_b32_e32 v36, 16, v97
	v_and_b32_e32 v37, 0xffff0000, v97
	v_lshlrev_b32_e32 v38, 16, v98
	v_and_b32_e32 v39, 0xffff0000, v98
	v_lshlrev_b32_e32 v40, 16, v99
	v_and_b32_e32 v41, 0xffff0000, v99
	v_pk_fma_f32 v[30:31], v[30:31], v[114:115], v[36:37]
	v_pk_fma_f32 v[28:29], v[28:29], v[112:113], v[34:35]
	v_pk_fma_f32 v[34:35], v[26:27], v[106:107], v[40:41]
	v_pk_fma_f32 v[26:27], v[24:25], v[104:105], v[38:39]
	v_cvt_pk_bf16_f32 v24, v28, v29
	v_cvt_pk_bf16_f32 v25, v30, v31
	v_add_u32_e32 v36, v241, v33
	v_cvt_pk_bf16_f32 v26, v26, v27
	v_cvt_pk_bf16_f32 v27, v34, v35
	global_store_dwordx4 v36, v[24:27], s[20:21]
	v_lshlrev_b32_e32 v28, 16, v24
	v_and_b32_e32 v29, 0xffff0000, v24
	v_lshlrev_b32_e32 v24, 16, v25
	v_and_b32_e32 v25, 0xffff0000, v25
	v_mul_f32_e32 v34, v29, v29
	v_mul_f32_e32 v35, v25, v25
	v_lshlrev_b32_e32 v30, 16, v26
	v_and_b32_e32 v31, 0xffff0000, v26
	v_lshlrev_b32_e32 v26, 16, v27
	v_and_b32_e32 v27, 0xffff0000, v27
	v_fmac_f32_e32 v34, v28, v28
	v_fmac_f32_e32 v35, v24, v24
	v_add_f32_e32 v34, v34, v35
	v_mul_f32_e32 v35, v31, v31
	v_mul_f32_e32 v37, v27, v27
	v_fmac_f32_e32 v35, v30, v30
	v_fmac_f32_e32 v37, v26, v26
	v_add_f32_e32 v35, v35, v37
	v_add_f32_e32 v37, v34, v35
	v_pk_mul_f32 v[34:35], v[102:103], v[24:25]
	v_pk_mul_f32 v[24:25], v[100:101], v[28:29]
	v_pk_mul_f32 v[28:29], v[94:95], v[26:27]
	v_pk_mul_f32 v[26:27], v[92:93], v[30:31]
	v_cvt_pk_bf16_f32 v24, v24, v25
	v_cvt_pk_bf16_f32 v25, v34, v35
	v_lshlrev_b32_e32 v34, 12, v32
	v_cvt_pk_bf16_f32 v26, v26, v27
	v_cvt_pk_bf16_f32 v27, v28, v29
	v_sub_u32_e32 v28, v36, v34
	s_cmp_eq_u32 s32, 3
	s_cbranch_scc1 .Lxg3_12
	global_store_dwordx4 v28, v[24:27], s[22:23] sc1
.Lxg3_12:
	v_lshlrev_b32_e32 v28, 16, v90
	v_and_b32_e32 v29, 0xffff0000, v90
	v_lshlrev_b32_e32 v24, 16, v88
	v_and_b32_e32 v25, 0xffff0000, v88
	v_lshlrev_b32_e32 v26, 16, v89
	v_and_b32_e32 v27, 0xffff0000, v89
	v_lshlrev_b32_e32 v30, 16, v91
	v_and_b32_e32 v31, 0xffff0000, v91
	v_pk_fma_f32 v[22:23], v[22:23], v[86:87], v[26:27]
	v_pk_fma_f32 v[20:21], v[20:21], v[84:85], v[24:25]
	v_pk_fma_f32 v[24:25], v[18:19], v[82:83], v[30:31]
	v_pk_fma_f32 v[18:19], v[16:17], v[80:81], v[28:29]
	v_cvt_pk_bf16_f32 v16, v20, v21
	v_cvt_pk_bf16_f32 v17, v22, v23
	v_add_u32_e32 v26, v144, v33
	v_cvt_pk_bf16_f32 v18, v18, v19
	v_cvt_pk_bf16_f32 v19, v24, v25
	global_store_dwordx4 v26, v[16:19], s[20:21]
	v_lshlrev_b32_e32 v20, 16, v16
	v_and_b32_e32 v21, 0xffff0000, v16
	v_lshlrev_b32_e32 v16, 16, v17
	v_and_b32_e32 v17, 0xffff0000, v17
	v_mul_f32_e32 v24, v21, v21
	v_mul_f32_e32 v25, v17, v17
	v_lshlrev_b32_e32 v22, 16, v18
	v_and_b32_e32 v23, 0xffff0000, v18
	v_lshlrev_b32_e32 v18, 16, v19
	v_and_b32_e32 v19, 0xffff0000, v19
	v_fmac_f32_e32 v24, v20, v20
	v_fmac_f32_e32 v25, v16, v16
	v_add_f32_e32 v24, v24, v25
	v_mul_f32_e32 v25, v23, v23
	v_mul_f32_e32 v27, v19, v19
	v_fmac_f32_e32 v25, v22, v22
	v_fmac_f32_e32 v27, v18, v18
	v_add_f32_e32 v25, v25, v27
	v_add_f32_e32 v24, v24, v25
	v_add_f32_e32 v27, v37, v24
	v_pk_mul_f32 v[24:25], v[78:79], v[16:17]
	v_pk_mul_f32 v[16:17], v[76:77], v[20:21]
	v_pk_mul_f32 v[20:21], v[70:71], v[18:19]
	v_pk_mul_f32 v[18:19], v[68:69], v[22:23]
	ds_swizzle_b32 v22, v27 offset:swizzle(SWAP,16)
	v_cvt_pk_bf16_f32 v16, v16, v17
	v_cvt_pk_bf16_f32 v17, v24, v25
	v_cvt_pk_bf16_f32 v18, v18, v19
	v_cvt_pk_bf16_f32 v19, v20, v21
	v_sub_u32_e32 v20, v26, v34
	s_cmp_eq_u32 s32, 3
	s_cbranch_scc1 .Lxg3_13
	global_store_dwordx4 v20, v[16:19], s[22:23] sc1

.LBB0_1307:
	s_or_b64 exec, exec, s[78:79]
	v_add_u32_e32 v16, 0xb0, v242
	v_lshlrev_b32_e32 v17, 13, v16
	v_lshlrev_b32_e32 v18, 16, v72
	v_and_b32_e32 v19, 0xffff0000, v72
	v_lshlrev_b32_e32 v20, 16, v73
	v_and_b32_e32 v21, 0xffff0000, v73
	v_lshlrev_b32_e32 v22, 16, v74
	v_and_b32_e32 v23, 0xffff0000, v74
	v_lshlrev_b32_e32 v24, 16, v75
	v_and_b32_e32 v25, 0xffff0000, v75
	v_pk_fma_f32 v[14:15], v[14:15], v[114:115], v[20:21]
	v_pk_fma_f32 v[12:13], v[12:13], v[112:113], v[18:19]
	v_pk_fma_f32 v[18:19], v[10:11], v[106:107], v[24:25]
	v_pk_fma_f32 v[10:11], v[8:9], v[104:105], v[22:23]
	v_cvt_pk_bf16_f32 v8, v12, v13
	v_cvt_pk_bf16_f32 v9, v14, v15
	v_add_u32_e32 v20, v241, v17
	v_cvt_pk_bf16_f32 v10, v10, v11
	v_cvt_pk_bf16_f32 v11, v18, v19
	global_store_dwordx4 v20, v[8:11], s[20:21]
	v_lshlrev_b32_e32 v12, 16, v8
	v_and_b32_e32 v13, 0xffff0000, v8
	v_lshlrev_b32_e32 v8, 16, v9
	v_and_b32_e32 v9, 0xffff0000, v9
	v_mul_f32_e32 v18, v13, v13
	v_mul_f32_e32 v19, v9, v9
	v_lshlrev_b32_e32 v14, 16, v10
	v_and_b32_e32 v15, 0xffff0000, v10
	v_lshlrev_b32_e32 v10, 16, v11
	v_and_b32_e32 v11, 0xffff0000, v11
	v_fmac_f32_e32 v18, v12, v12
	v_fmac_f32_e32 v19, v8, v8
	v_add_f32_e32 v18, v18, v19
	v_mul_f32_e32 v19, v15, v15
	v_mul_f32_e32 v21, v11, v11
	v_fmac_f32_e32 v19, v14, v14
	v_fmac_f32_e32 v21, v10, v10
	v_add_f32_e32 v19, v19, v21
	v_add_f32_e32 v21, v18, v19
	v_pk_mul_f32 v[18:19], v[102:103], v[8:9]
	v_pk_mul_f32 v[8:9], v[100:101], v[12:13]
	v_pk_mul_f32 v[12:13], v[94:95], v[10:11]
	v_pk_mul_f32 v[10:11], v[92:93], v[14:15]
	v_cvt_pk_bf16_f32 v8, v8, v9
	v_cvt_pk_bf16_f32 v9, v18, v19
	v_lshlrev_b32_e32 v18, 12, v16
	v_cvt_pk_bf16_f32 v10, v10, v11
	v_cvt_pk_bf16_f32 v11, v12, v13
	v_sub_u32_e32 v12, v20, v18
	s_cmp_eq_u32 s32, 3
	s_cbranch_scc1 .Lxg3_14
	global_store_dwordx4 v12, v[8:11], s[22:23] sc1
.Lxg3_14:
	v_lshlrev_b32_e32 v12, 16, v66
	v_and_b32_e32 v13, 0xffff0000, v66
	v_lshlrev_b32_e32 v8, 16, v64
	v_and_b32_e32 v9, 0xffff0000, v64
	v_lshlrev_b32_e32 v10, 16, v65
	v_and_b32_e32 v11, 0xffff0000, v65
	v_lshlrev_b32_e32 v14, 16, v67
	v_and_b32_e32 v15, 0xffff0000, v67
	v_pk_fma_f32 v[6:7], v[6:7], v[86:87], v[10:11]
	v_pk_fma_f32 v[4:5], v[4:5], v[84:85], v[8:9]
	v_pk_fma_f32 v[8:9], v[2:3], v[82:83], v[14:15]
	v_pk_fma_f32 v[2:3], v[0:1], v[80:81], v[12:13]
	v_cvt_pk_bf16_f32 v0, v4, v5
	v_cvt_pk_bf16_f32 v1, v6, v7
	v_add_u32_e32 v10, v144, v17
	v_cvt_pk_bf16_f32 v2, v2, v3
	v_cvt_pk_bf16_f32 v3, v8, v9
	global_store_dwordx4 v10, v[0:3], s[20:21]
	v_lshlrev_b32_e32 v4, 16, v0
	v_and_b32_e32 v5, 0xffff0000, v0
	v_lshlrev_b32_e32 v0, 16, v1
	v_and_b32_e32 v1, 0xffff0000, v1
	v_mul_f32_e32 v8, v5, v5
	v_mul_f32_e32 v9, v1, v1
	v_lshlrev_b32_e32 v6, 16, v2
	v_and_b32_e32 v7, 0xffff0000, v2
	v_lshlrev_b32_e32 v2, 16, v3
	v_and_b32_e32 v3, 0xffff0000, v3
	v_fmac_f32_e32 v8, v4, v4
	v_fmac_f32_e32 v9, v0, v0
	v_add_f32_e32 v8, v8, v9
	v_mul_f32_e32 v9, v7, v7
	v_mul_f32_e32 v11, v3, v3
	v_fmac_f32_e32 v9, v6, v6
	v_fmac_f32_e32 v11, v2, v2
	v_add_f32_e32 v9, v9, v11
	v_add_f32_e32 v8, v8, v9
	v_add_f32_e32 v11, v21, v8
	v_pk_mul_f32 v[8:9], v[78:79], v[0:1]
	v_pk_mul_f32 v[0:1], v[76:77], v[4:5]
	v_pk_mul_f32 v[4:5], v[70:71], v[2:3]
	v_pk_mul_f32 v[2:3], v[68:69], v[6:7]
	ds_swizzle_b32 v6, v11 offset:swizzle(SWAP,16)
	v_cvt_pk_bf16_f32 v0, v0, v1
	v_cvt_pk_bf16_f32 v1, v8, v9
	v_cvt_pk_bf16_f32 v2, v2, v3
	v_cvt_pk_bf16_f32 v3, v4, v5
	v_sub_u32_e32 v4, v10, v18
	s_cmp_eq_u32 s32, 3
	s_cbranch_scc1 .Lxg3_15
	global_store_dwordx4 v4, v[0:3], s[22:23] sc1
